# speedup vs baseline: 1.0920x; 1.0156x over previous
.Lpv_loop:
	v_mad_u64_u32 v[248:249], vcc, v250, s0, v[86:87]
	global_load_dwordx4 v[244:247], v[248:249], off
	global_load_dwordx4 v[228:231], v[248:249], off offset:256
	ds_read_b32 v227, v131 offset:0
	ds_read_b32 v130, v132 offset:0
	s_waitcnt vmcnt(15)
	v_cvt_scalef32_pk_f32_fp4 v[134:135], v10, 1.0
	v_cvt_scalef32_pk_f32_fp4 v[136:137], v10, 1.0 op_sel:[1,0,0]
	v_cvt_scalef32_pk_f32_fp4 v[138:139], v10, 1.0 op_sel:[0,1,0]
	v_cvt_scalef32_pk_f32_fp4 v[140:141], v10, 1.0 op_sel:[1,1,0]
	s_waitcnt lgkmcnt(0)
	v_pk_fma_f32 v[128:129], v[130:131], v[134:135], v[128:129] op_sel_hi:[0,1,1]
	v_pk_fma_f32 v[126:127], v[130:131], v[136:137], v[126:127] op_sel_hi:[0,1,1]
	v_pk_fma_f32 v[122:123], v[130:131], v[138:139], v[122:123] op_sel_hi:[0,1,1]
	v_pk_fma_f32 v[120:121], v[130:131], v[140:141], v[120:121] op_sel_hi:[0,1,1]
	v_cvt_scalef32_pk_f32_fp4 v[134:135], v11, 1.0
	v_cvt_scalef32_pk_f32_fp4 v[136:137], v11, 1.0 op_sel:[1,0,0]
	v_cvt_scalef32_pk_f32_fp4 v[138:139], v11, 1.0 op_sel:[0,1,0]
	v_cvt_scalef32_pk_f32_fp4 v[140:141], v11, 1.0 op_sel:[1,1,0]
	v_pk_fma_f32 v[118:119], v[130:131], v[134:135], v[118:119] op_sel_hi:[0,1,1]
	v_pk_fma_f32 v[116:117], v[130:131], v[136:137], v[116:117] op_sel_hi:[0,1,1]
	v_pk_fma_f32 v[114:115], v[130:131], v[138:139], v[114:115] op_sel_hi:[0,1,1]
	v_pk_fma_f32 v[112:113], v[130:131], v[140:141], v[112:113] op_sel_hi:[0,1,1]
	v_cvt_scalef32_pk_f32_fp4 v[134:135], v12, 1.0
	v_cvt_scalef32_pk_f32_fp4 v[136:137], v12, 1.0 op_sel:[1,0,0]
	v_cvt_scalef32_pk_f32_fp4 v[138:139], v12, 1.0 op_sel:[0,1,0]
	v_cvt_scalef32_pk_f32_fp4 v[140:141], v12, 1.0 op_sel:[1,1,0]
	v_pk_fma_f32 v[80:81], v[130:131], v[134:135], v[80:81] op_sel_hi:[0,1,1]
	v_pk_fma_f32 v[78:79], v[130:131], v[136:137], v[78:79] op_sel_hi:[0,1,1]
	v_pk_fma_f32 v[76:77], v[130:131], v[138:139], v[76:77] op_sel_hi:[0,1,1]
	v_pk_fma_f32 v[74:75], v[130:131], v[140:141], v[74:75] op_sel_hi:[0,1,1]
	v_cvt_scalef32_pk_f32_fp4 v[134:135], v13, 1.0
	v_cvt_scalef32_pk_f32_fp4 v[136:137], v13, 1.0 op_sel:[1,0,0]
	v_cvt_scalef32_pk_f32_fp4 v[138:139], v13, 1.0 op_sel:[0,1,0]
	v_cvt_scalef32_pk_f32_fp4 v[140:141], v13, 1.0 op_sel:[1,1,0]
	v_pk_fma_f32 v[72:73], v[130:131], v[134:135], v[72:73] op_sel_hi:[0,1,1]
	v_pk_fma_f32 v[70:71], v[130:131], v[136:137], v[70:71] op_sel_hi:[0,1,1]
	v_pk_fma_f32 v[68:69], v[130:131], v[138:139], v[68:69] op_sel_hi:[0,1,1]
	v_pk_fma_f32 v[66:67], v[130:131], v[140:141], v[66:67] op_sel_hi:[0,1,1]
	s_waitcnt vmcnt(14)
	v_cvt_scalef32_pk_f32_fp4 v[134:135], v2, 1.0
	v_cvt_scalef32_pk_f32_fp4 v[136:137], v2, 1.0 op_sel:[1,0,0]
	v_cvt_scalef32_pk_f32_fp4 v[138:139], v2, 1.0 op_sel:[0,1,0]
	v_cvt_scalef32_pk_f32_fp4 v[140:141], v2, 1.0 op_sel:[1,1,0]
	v_pk_fma_f32 v[34:35], v[130:131], v[134:135], v[34:35] op_sel_hi:[0,1,1]
	v_pk_fma_f32 v[36:37], v[130:131], v[136:137], v[36:37] op_sel_hi:[0,1,1]
	v_pk_fma_f32 v[38:39], v[130:131], v[138:139], v[38:39] op_sel_hi:[0,1,1]
	v_pk_fma_f32 v[40:41], v[130:131], v[140:141], v[40:41] op_sel_hi:[0,1,1]
	v_cvt_scalef32_pk_f32_fp4 v[134:135], v3, 1.0
	v_cvt_scalef32_pk_f32_fp4 v[136:137], v3, 1.0 op_sel:[1,0,0]
	v_cvt_scalef32_pk_f32_fp4 v[138:139], v3, 1.0 op_sel:[0,1,0]
	v_cvt_scalef32_pk_f32_fp4 v[140:141], v3, 1.0 op_sel:[1,1,0]
	v_pk_fma_f32 v[42:43], v[130:131], v[134:135], v[42:43] op_sel_hi:[0,1,1]
	v_pk_fma_f32 v[44:45], v[130:131], v[136:137], v[44:45] op_sel_hi:[0,1,1]
	v_pk_fma_f32 v[46:47], v[130:131], v[138:139], v[46:47] op_sel_hi:[0,1,1]
	v_pk_fma_f32 v[48:49], v[130:131], v[140:141], v[48:49] op_sel_hi:[0,1,1]
	v_cvt_scalef32_pk_f32_fp4 v[134:135], v4, 1.0
	v_cvt_scalef32_pk_f32_fp4 v[136:137], v4, 1.0 op_sel:[1,0,0]
	v_cvt_scalef32_pk_f32_fp4 v[138:139], v4, 1.0 op_sel:[0,1,0]
	v_cvt_scalef32_pk_f32_fp4 v[140:141], v4, 1.0 op_sel:[1,1,0]
	v_pk_fma_f32 v[50:51], v[130:131], v[134:135], v[50:51] op_sel_hi:[0,1,1]
	v_pk_fma_f32 v[52:53], v[130:131], v[136:137], v[52:53] op_sel_hi:[0,1,1]
	v_pk_fma_f32 v[54:55], v[130:131], v[138:139], v[54:55] op_sel_hi:[0,1,1]
	v_pk_fma_f32 v[56:57], v[130:131], v[140:141], v[56:57] op_sel_hi:[0,1,1]
	v_cvt_scalef32_pk_f32_fp4 v[134:135], v5, 1.0
	v_cvt_scalef32_pk_f32_fp4 v[136:137], v5, 1.0 op_sel:[1,0,0]
	v_cvt_scalef32_pk_f32_fp4 v[138:139], v5, 1.0 op_sel:[0,1,0]
	v_cvt_scalef32_pk_f32_fp4 v[140:141], v5, 1.0 op_sel:[1,1,0]
	v_pk_fma_f32 v[58:59], v[130:131], v[134:135], v[58:59] op_sel_hi:[0,1,1]
	v_pk_fma_f32 v[60:61], v[130:131], v[136:137], v[60:61] op_sel_hi:[0,1,1]
	v_pk_fma_f32 v[62:63], v[130:131], v[138:139], v[62:63] op_sel_hi:[0,1,1]
	v_pk_fma_f32 v[64:65], v[130:131], v[140:141], v[64:65] op_sel_hi:[0,1,1]
	v_mad_u64_u32 v[248:249], vcc, v227, s0, v[86:87]
	global_load_dwordx4 v[10:13], v[248:249], off
	global_load_dwordx4 v[2:5], v[248:249], off offset:256
	ds_read_b32 v250, v131 offset:16
	ds_read_b32 v130, v132 offset:16
	s_waitcnt vmcnt(15)
	v_cvt_scalef32_pk_f32_fp4 v[134:135], v14, 1.0
	v_cvt_scalef32_pk_f32_fp4 v[136:137], v14, 1.0 op_sel:[1,0,0]
	v_cvt_scalef32_pk_f32_fp4 v[138:139], v14, 1.0 op_sel:[0,1,0]
	v_cvt_scalef32_pk_f32_fp4 v[140:141], v14, 1.0 op_sel:[1,1,0]
	s_waitcnt lgkmcnt(0)
	v_pk_fma_f32 v[128:129], v[130:131], v[134:135], v[128:129] op_sel_hi:[0,1,1]
	v_pk_fma_f32 v[126:127], v[130:131], v[136:137], v[126:127] op_sel_hi:[0,1,1]
	v_pk_fma_f32 v[122:123], v[130:131], v[138:139], v[122:123] op_sel_hi:[0,1,1]
	v_pk_fma_f32 v[120:121], v[130:131], v[140:141], v[120:121] op_sel_hi:[0,1,1]
	v_cvt_scalef32_pk_f32_fp4 v[134:135], v15, 1.0
	v_cvt_scalef32_pk_f32_fp4 v[136:137], v15, 1.0 op_sel:[1,0,0]
	v_cvt_scalef32_pk_f32_fp4 v[138:139], v15, 1.0 op_sel:[0,1,0]
	v_cvt_scalef32_pk_f32_fp4 v[140:141], v15, 1.0 op_sel:[1,1,0]
	v_pk_fma_f32 v[118:119], v[130:131], v[134:135], v[118:119] op_sel_hi:[0,1,1]
	v_pk_fma_f32 v[116:117], v[130:131], v[136:137], v[116:117] op_sel_hi:[0,1,1]
	v_pk_fma_f32 v[114:115], v[130:131], v[138:139], v[114:115] op_sel_hi:[0,1,1]
	v_pk_fma_f32 v[112:113], v[130:131], v[140:141], v[112:113] op_sel_hi:[0,1,1]
	v_cvt_scalef32_pk_f32_fp4 v[134:135], v16, 1.0
	v_cvt_scalef32_pk_f32_fp4 v[136:137], v16, 1.0 op_sel:[1,0,0]
	v_cvt_scalef32_pk_f32_fp4 v[138:139], v16, 1.0 op_sel:[0,1,0]
	v_cvt_scalef32_pk_f32_fp4 v[140:141], v16, 1.0 op_sel:[1,1,0]
	v_pk_fma_f32 v[80:81], v[130:131], v[134:135], v[80:81] op_sel_hi:[0,1,1]
	v_pk_fma_f32 v[78:79], v[130:131], v[136:137], v[78:79] op_sel_hi:[0,1,1]
	v_pk_fma_f32 v[76:77], v[130:131], v[138:139], v[76:77] op_sel_hi:[0,1,1]
	v_pk_fma_f32 v[74:75], v[130:131], v[140:141], v[74:75] op_sel_hi:[0,1,1]
	v_cvt_scalef32_pk_f32_fp4 v[134:135], v17, 1.0
	v_cvt_scalef32_pk_f32_fp4 v[136:137], v17, 1.0 op_sel:[1,0,0]
	v_cvt_scalef32_pk_f32_fp4 v[138:139], v17, 1.0 op_sel:[0,1,0]
	v_cvt_scalef32_pk_f32_fp4 v[140:141], v17, 1.0 op_sel:[1,1,0]
	v_pk_fma_f32 v[72:73], v[130:131], v[134:135], v[72:73] op_sel_hi:[0,1,1]
	v_pk_fma_f32 v[70:71], v[130:131], v[136:137], v[70:71] op_sel_hi:[0,1,1]
	v_pk_fma_f32 v[68:69], v[130:131], v[138:139], v[68:69] op_sel_hi:[0,1,1]
	v_pk_fma_f32 v[66:67], v[130:131], v[140:141], v[66:67] op_sel_hi:[0,1,1]
	s_waitcnt vmcnt(14)
	v_cvt_scalef32_pk_f32_fp4 v[134:135], v6, 1.0
	v_cvt_scalef32_pk_f32_fp4 v[136:137], v6, 1.0 op_sel:[1,0,0]
	v_cvt_scalef32_pk_f32_fp4 v[138:139], v6, 1.0 op_sel:[0,1,0]
	v_cvt_scalef32_pk_f32_fp4 v[140:141], v6, 1.0 op_sel:[1,1,0]
	v_pk_fma_f32 v[34:35], v[130:131], v[134:135], v[34:35] op_sel_hi:[0,1,1]
	v_pk_fma_f32 v[36:37], v[130:131], v[136:137], v[36:37] op_sel_hi:[0,1,1]
	v_pk_fma_f32 v[38:39], v[130:131], v[138:139], v[38:39] op_sel_hi:[0,1,1]
	v_pk_fma_f32 v[40:41], v[130:131], v[140:141], v[40:41] op_sel_hi:[0,1,1]
	v_cvt_scalef32_pk_f32_fp4 v[134:135], v7, 1.0
	v_cvt_scalef32_pk_f32_fp4 v[136:137], v7, 1.0 op_sel:[1,0,0]
	v_cvt_scalef32_pk_f32_fp4 v[138:139], v7, 1.0 op_sel:[0,1,0]
	v_cvt_scalef32_pk_f32_fp4 v[140:141], v7, 1.0 op_sel:[1,1,0]
	v_pk_fma_f32 v[42:43], v[130:131], v[134:135], v[42:43] op_sel_hi:[0,1,1]
	v_pk_fma_f32 v[44:45], v[130:131], v[136:137], v[44:45] op_sel_hi:[0,1,1]
	v_pk_fma_f32 v[46:47], v[130:131], v[138:139], v[46:47] op_sel_hi:[0,1,1]
	v_pk_fma_f32 v[48:49], v[130:131], v[140:141], v[48:49] op_sel_hi:[0,1,1]
	v_cvt_scalef32_pk_f32_fp4 v[134:135], v8, 1.0
	v_cvt_scalef32_pk_f32_fp4 v[136:137], v8, 1.0 op_sel:[1,0,0]
	v_cvt_scalef32_pk_f32_fp4 v[138:139], v8, 1.0 op_sel:[0,1,0]
	v_cvt_scalef32_pk_f32_fp4 v[140:141], v8, 1.0 op_sel:[1,1,0]
	v_pk_fma_f32 v[50:51], v[130:131], v[134:135], v[50:51] op_sel_hi:[0,1,1]
	v_pk_fma_f32 v[52:53], v[130:131], v[136:137], v[52:53] op_sel_hi:[0,1,1]
	v_pk_fma_f32 v[54:55], v[130:131], v[138:139], v[54:55] op_sel_hi:[0,1,1]
	v_pk_fma_f32 v[56:57], v[130:131], v[140:141], v[56:57] op_sel_hi:[0,1,1]
	v_cvt_scalef32_pk_f32_fp4 v[134:135], v9, 1.0
	v_cvt_scalef32_pk_f32_fp4 v[136:137], v9, 1.0 op_sel:[1,0,0]
	v_cvt_scalef32_pk_f32_fp4 v[138:139], v9, 1.0 op_sel:[0,1,0]
	v_cvt_scalef32_pk_f32_fp4 v[140:141], v9, 1.0 op_sel:[1,1,0]
	v_pk_fma_f32 v[58:59], v[130:131], v[134:135], v[58:59] op_sel_hi:[0,1,1]
	v_pk_fma_f32 v[60:61], v[130:131], v[136:137], v[60:61] op_sel_hi:[0,1,1]
	v_pk_fma_f32 v[62:63], v[130:131], v[138:139], v[62:63] op_sel_hi:[0,1,1]
	v_pk_fma_f32 v[64:65], v[130:131], v[140:141], v[64:65] op_sel_hi:[0,1,1]
	v_mad_u64_u32 v[248:249], vcc, v250, s0, v[86:87]
	global_load_dwordx4 v[14:17], v[248:249], off
	global_load_dwordx4 v[6:9], v[248:249], off offset:256
	ds_read_b32 v227, v131 offset:32
	ds_read_b32 v130, v132 offset:32
	s_waitcnt vmcnt(15)
	v_cvt_scalef32_pk_f32_fp4 v[134:135], v22, 1.0
	v_cvt_scalef32_pk_f32_fp4 v[136:137], v22, 1.0 op_sel:[1,0,0]
	v_cvt_scalef32_pk_f32_fp4 v[138:139], v22, 1.0 op_sel:[0,1,0]
	v_cvt_scalef32_pk_f32_fp4 v[140:141], v22, 1.0 op_sel:[1,1,0]
	s_waitcnt lgkmcnt(0)
	v_pk_fma_f32 v[128:129], v[130:131], v[134:135], v[128:129] op_sel_hi:[0,1,1]
	v_pk_fma_f32 v[126:127], v[130:131], v[136:137], v[126:127] op_sel_hi:[0,1,1]
	v_pk_fma_f32 v[122:123], v[130:131], v[138:139], v[122:123] op_sel_hi:[0,1,1]
	v_pk_fma_f32 v[120:121], v[130:131], v[140:141], v[120:121] op_sel_hi:[0,1,1]
	v_cvt_scalef32_pk_f32_fp4 v[134:135], v23, 1.0
	v_cvt_scalef32_pk_f32_fp4 v[136:137], v23, 1.0 op_sel:[1,0,0]
	v_cvt_scalef32_pk_f32_fp4 v[138:139], v23, 1.0 op_sel:[0,1,0]
	v_cvt_scalef32_pk_f32_fp4 v[140:141], v23, 1.0 op_sel:[1,1,0]
	v_pk_fma_f32 v[118:119], v[130:131], v[134:135], v[118:119] op_sel_hi:[0,1,1]
	v_pk_fma_f32 v[116:117], v[130:131], v[136:137], v[116:117] op_sel_hi:[0,1,1]
	v_pk_fma_f32 v[114:115], v[130:131], v[138:139], v[114:115] op_sel_hi:[0,1,1]
	v_pk_fma_f32 v[112:113], v[130:131], v[140:141], v[112:113] op_sel_hi:[0,1,1]
	v_cvt_scalef32_pk_f32_fp4 v[134:135], v24, 1.0
	v_cvt_scalef32_pk_f32_fp4 v[136:137], v24, 1.0 op_sel:[1,0,0]
	v_cvt_scalef32_pk_f32_fp4 v[138:139], v24, 1.0 op_sel:[0,1,0]
	v_cvt_scalef32_pk_f32_fp4 v[140:141], v24, 1.0 op_sel:[1,1,0]
	v_pk_fma_f32 v[80:81], v[130:131], v[134:135], v[80:81] op_sel_hi:[0,1,1]
	v_pk_fma_f32 v[78:79], v[130:131], v[136:137], v[78:79] op_sel_hi:[0,1,1]
	v_pk_fma_f32 v[76:77], v[130:131], v[138:139], v[76:77] op_sel_hi:[0,1,1]
	v_pk_fma_f32 v[74:75], v[130:131], v[140:141], v[74:75] op_sel_hi:[0,1,1]
	v_cvt_scalef32_pk_f32_fp4 v[134:135], v25, 1.0
	v_cvt_scalef32_pk_f32_fp4 v[136:137], v25, 1.0 op_sel:[1,0,0]
	v_cvt_scalef32_pk_f32_fp4 v[138:139], v25, 1.0 op_sel:[0,1,0]
	v_cvt_scalef32_pk_f32_fp4 v[140:141], v25, 1.0 op_sel:[1,1,0]
	v_pk_fma_f32 v[72:73], v[130:131], v[134:135], v[72:73] op_sel_hi:[0,1,1]
	v_pk_fma_f32 v[70:71], v[130:131], v[136:137], v[70:71] op_sel_hi:[0,1,1]
	v_pk_fma_f32 v[68:69], v[130:131], v[138:139], v[68:69] op_sel_hi:[0,1,1]
	v_pk_fma_f32 v[66:67], v[130:131], v[140:141], v[66:67] op_sel_hi:[0,1,1]
	s_waitcnt vmcnt(14)
	v_cvt_scalef32_pk_f32_fp4 v[134:135], v18, 1.0
	v_cvt_scalef32_pk_f32_fp4 v[136:137], v18, 1.0 op_sel:[1,0,0]
	v_cvt_scalef32_pk_f32_fp4 v[138:139], v18, 1.0 op_sel:[0,1,0]
	v_cvt_scalef32_pk_f32_fp4 v[140:141], v18, 1.0 op_sel:[1,1,0]
	v_pk_fma_f32 v[34:35], v[130:131], v[134:135], v[34:35] op_sel_hi:[0,1,1]
	v_pk_fma_f32 v[36:37], v[130:131], v[136:137], v[36:37] op_sel_hi:[0,1,1]
	v_pk_fma_f32 v[38:39], v[130:131], v[138:139], v[38:39] op_sel_hi:[0,1,1]
	v_pk_fma_f32 v[40:41], v[130:131], v[140:141], v[40:41] op_sel_hi:[0,1,1]
	v_cvt_scalef32_pk_f32_fp4 v[134:135], v19, 1.0
	v_cvt_scalef32_pk_f32_fp4 v[136:137], v19, 1.0 op_sel:[1,0,0]
	v_cvt_scalef32_pk_f32_fp4 v[138:139], v19, 1.0 op_sel:[0,1,0]
	v_cvt_scalef32_pk_f32_fp4 v[140:141], v19, 1.0 op_sel:[1,1,0]
	v_pk_fma_f32 v[42:43], v[130:131], v[134:135], v[42:43] op_sel_hi:[0,1,1]
	v_pk_fma_f32 v[44:45], v[130:131], v[136:137], v[44:45] op_sel_hi:[0,1,1]
	v_pk_fma_f32 v[46:47], v[130:131], v[138:139], v[46:47] op_sel_hi:[0,1,1]
	v_pk_fma_f32 v[48:49], v[130:131], v[140:141], v[48:49] op_sel_hi:[0,1,1]
	v_cvt_scalef32_pk_f32_fp4 v[134:135], v20, 1.0
	v_cvt_scalef32_pk_f32_fp4 v[136:137], v20, 1.0 op_sel:[1,0,0]
	v_cvt_scalef32_pk_f32_fp4 v[138:139], v20, 1.0 op_sel:[0,1,0]
	v_cvt_scalef32_pk_f32_fp4 v[140:141], v20, 1.0 op_sel:[1,1,0]
	v_pk_fma_f32 v[50:51], v[130:131], v[134:135], v[50:51] op_sel_hi:[0,1,1]
	v_pk_fma_f32 v[52:53], v[130:131], v[136:137], v[52:53] op_sel_hi:[0,1,1]
	v_pk_fma_f32 v[54:55], v[130:131], v[138:139], v[54:55] op_sel_hi:[0,1,1]
	v_pk_fma_f32 v[56:57], v[130:131], v[140:141], v[56:57] op_sel_hi:[0,1,1]
	v_cvt_scalef32_pk_f32_fp4 v[134:135], v21, 1.0
	v_cvt_scalef32_pk_f32_fp4 v[136:137], v21, 1.0 op_sel:[1,0,0]
	v_cvt_scalef32_pk_f32_fp4 v[138:139], v21, 1.0 op_sel:[0,1,0]
	v_cvt_scalef32_pk_f32_fp4 v[140:141], v21, 1.0 op_sel:[1,1,0]
	v_pk_fma_f32 v[58:59], v[130:131], v[134:135], v[58:59] op_sel_hi:[0,1,1]
	v_pk_fma_f32 v[60:61], v[130:131], v[136:137], v[60:61] op_sel_hi:[0,1,1]
	v_pk_fma_f32 v[62:63], v[130:131], v[138:139], v[62:63] op_sel_hi:[0,1,1]
	v_pk_fma_f32 v[64:65], v[130:131], v[140:141], v[64:65] op_sel_hi:[0,1,1]
	v_mad_u64_u32 v[248:249], vcc, v227, s0, v[86:87]
	global_load_dwordx4 v[22:25], v[248:249], off
	global_load_dwordx4 v[18:21], v[248:249], off offset:256
	ds_read_b32 v250, v131 offset:48
	ds_read_b32 v130, v132 offset:48
	s_waitcnt vmcnt(15)
	v_cvt_scalef32_pk_f32_fp4 v[134:135], v30, 1.0
	v_cvt_scalef32_pk_f32_fp4 v[136:137], v30, 1.0 op_sel:[1,0,0]
	v_cvt_scalef32_pk_f32_fp4 v[138:139], v30, 1.0 op_sel:[0,1,0]
	v_cvt_scalef32_pk_f32_fp4 v[140:141], v30, 1.0 op_sel:[1,1,0]
	s_waitcnt lgkmcnt(0)
	v_pk_fma_f32 v[128:129], v[130:131], v[134:135], v[128:129] op_sel_hi:[0,1,1]
	v_pk_fma_f32 v[126:127], v[130:131], v[136:137], v[126:127] op_sel_hi:[0,1,1]
	v_pk_fma_f32 v[122:123], v[130:131], v[138:139], v[122:123] op_sel_hi:[0,1,1]
	v_pk_fma_f32 v[120:121], v[130:131], v[140:141], v[120:121] op_sel_hi:[0,1,1]
	v_cvt_scalef32_pk_f32_fp4 v[134:135], v31, 1.0
	v_cvt_scalef32_pk_f32_fp4 v[136:137], v31, 1.0 op_sel:[1,0,0]
	v_cvt_scalef32_pk_f32_fp4 v[138:139], v31, 1.0 op_sel:[0,1,0]
	v_cvt_scalef32_pk_f32_fp4 v[140:141], v31, 1.0 op_sel:[1,1,0]
	v_pk_fma_f32 v[118:119], v[130:131], v[134:135], v[118:119] op_sel_hi:[0,1,1]
	v_pk_fma_f32 v[116:117], v[130:131], v[136:137], v[116:117] op_sel_hi:[0,1,1]
	v_pk_fma_f32 v[114:115], v[130:131], v[138:139], v[114:115] op_sel_hi:[0,1,1]
	v_pk_fma_f32 v[112:113], v[130:131], v[140:141], v[112:113] op_sel_hi:[0,1,1]
	v_cvt_scalef32_pk_f32_fp4 v[134:135], v32, 1.0
	v_cvt_scalef32_pk_f32_fp4 v[136:137], v32, 1.0 op_sel:[1,0,0]
	v_cvt_scalef32_pk_f32_fp4 v[138:139], v32, 1.0 op_sel:[0,1,0]
	v_cvt_scalef32_pk_f32_fp4 v[140:141], v32, 1.0 op_sel:[1,1,0]
	v_pk_fma_f32 v[80:81], v[130:131], v[134:135], v[80:81] op_sel_hi:[0,1,1]
	v_pk_fma_f32 v[78:79], v[130:131], v[136:137], v[78:79] op_sel_hi:[0,1,1]
	v_pk_fma_f32 v[76:77], v[130:131], v[138:139], v[76:77] op_sel_hi:[0,1,1]
	v_pk_fma_f32 v[74:75], v[130:131], v[140:141], v[74:75] op_sel_hi:[0,1,1]
	v_cvt_scalef32_pk_f32_fp4 v[134:135], v33, 1.0
	v_cvt_scalef32_pk_f32_fp4 v[136:137], v33, 1.0 op_sel:[1,0,0]
	v_cvt_scalef32_pk_f32_fp4 v[138:139], v33, 1.0 op_sel:[0,1,0]
	v_cvt_scalef32_pk_f32_fp4 v[140:141], v33, 1.0 op_sel:[1,1,0]
	v_pk_fma_f32 v[72:73], v[130:131], v[134:135], v[72:73] op_sel_hi:[0,1,1]
	v_pk_fma_f32 v[70:71], v[130:131], v[136:137], v[70:71] op_sel_hi:[0,1,1]
	v_pk_fma_f32 v[68:69], v[130:131], v[138:139], v[68:69] op_sel_hi:[0,1,1]
	v_pk_fma_f32 v[66:67], v[130:131], v[140:141], v[66:67] op_sel_hi:[0,1,1]
	s_waitcnt vmcnt(14)
	v_cvt_scalef32_pk_f32_fp4 v[134:135], v26, 1.0
	v_cvt_scalef32_pk_f32_fp4 v[136:137], v26, 1.0 op_sel:[1,0,0]
	v_cvt_scalef32_pk_f32_fp4 v[138:139], v26, 1.0 op_sel:[0,1,0]
	v_cvt_scalef32_pk_f32_fp4 v[140:141], v26, 1.0 op_sel:[1,1,0]
	v_pk_fma_f32 v[34:35], v[130:131], v[134:135], v[34:35] op_sel_hi:[0,1,1]
	v_pk_fma_f32 v[36:37], v[130:131], v[136:137], v[36:37] op_sel_hi:[0,1,1]
	v_pk_fma_f32 v[38:39], v[130:131], v[138:139], v[38:39] op_sel_hi:[0,1,1]
	v_pk_fma_f32 v[40:41], v[130:131], v[140:141], v[40:41] op_sel_hi:[0,1,1]
	v_cvt_scalef32_pk_f32_fp4 v[134:135], v27, 1.0
	v_cvt_scalef32_pk_f32_fp4 v[136:137], v27, 1.0 op_sel:[1,0,0]
	v_cvt_scalef32_pk_f32_fp4 v[138:139], v27, 1.0 op_sel:[0,1,0]
	v_cvt_scalef32_pk_f32_fp4 v[140:141], v27, 1.0 op_sel:[1,1,0]
	v_pk_fma_f32 v[42:43], v[130:131], v[134:135], v[42:43] op_sel_hi:[0,1,1]
	v_pk_fma_f32 v[44:45], v[130:131], v[136:137], v[44:45] op_sel_hi:[0,1,1]
	v_pk_fma_f32 v[46:47], v[130:131], v[138:139], v[46:47] op_sel_hi:[0,1,1]
	v_pk_fma_f32 v[48:49], v[130:131], v[140:141], v[48:49] op_sel_hi:[0,1,1]
	v_cvt_scalef32_pk_f32_fp4 v[134:135], v28, 1.0
	v_cvt_scalef32_pk_f32_fp4 v[136:137], v28, 1.0 op_sel:[1,0,0]
	v_cvt_scalef32_pk_f32_fp4 v[138:139], v28, 1.0 op_sel:[0,1,0]
	v_cvt_scalef32_pk_f32_fp4 v[140:141], v28, 1.0 op_sel:[1,1,0]
	v_pk_fma_f32 v[50:51], v[130:131], v[134:135], v[50:51] op_sel_hi:[0,1,1]
	v_pk_fma_f32 v[52:53], v[130:131], v[136:137], v[52:53] op_sel_hi:[0,1,1]
	v_pk_fma_f32 v[54:55], v[130:131], v[138:139], v[54:55] op_sel_hi:[0,1,1]
	v_pk_fma_f32 v[56:57], v[130:131], v[140:141], v[56:57] op_sel_hi:[0,1,1]
	v_cvt_scalef32_pk_f32_fp4 v[134:135], v29, 1.0
	v_cvt_scalef32_pk_f32_fp4 v[136:137], v29, 1.0 op_sel:[1,0,0]
	v_cvt_scalef32_pk_f32_fp4 v[138:139], v29, 1.0 op_sel:[0,1,0]
	v_cvt_scalef32_pk_f32_fp4 v[140:141], v29, 1.0 op_sel:[1,1,0]
	v_pk_fma_f32 v[58:59], v[130:131], v[134:135], v[58:59] op_sel_hi:[0,1,1]
	v_pk_fma_f32 v[60:61], v[130:131], v[136:137], v[60:61] op_sel_hi:[0,1,1]
	v_pk_fma_f32 v[62:63], v[130:131], v[138:139], v[62:63] op_sel_hi:[0,1,1]
	v_pk_fma_f32 v[64:65], v[130:131], v[140:141], v[64:65] op_sel_hi:[0,1,1]
	v_mad_u64_u32 v[248:249], vcc, v250, s0, v[86:87]
	global_load_dwordx4 v[30:33], v[248:249], off
	global_load_dwordx4 v[26:29], v[248:249], off offset:256
	ds_read_b32 v227, v131 offset:64
	ds_read_b32 v130, v132 offset:64
	s_waitcnt vmcnt(15)
	v_cvt_scalef32_pk_f32_fp4 v[134:135], v142, 1.0
	v_cvt_scalef32_pk_f32_fp4 v[136:137], v142, 1.0 op_sel:[1,0,0]
	v_cvt_scalef32_pk_f32_fp4 v[138:139], v142, 1.0 op_sel:[0,1,0]
	v_cvt_scalef32_pk_f32_fp4 v[140:141], v142, 1.0 op_sel:[1,1,0]
	s_waitcnt lgkmcnt(0)
	v_pk_fma_f32 v[128:129], v[130:131], v[134:135], v[128:129] op_sel_hi:[0,1,1]
	v_pk_fma_f32 v[126:127], v[130:131], v[136:137], v[126:127] op_sel_hi:[0,1,1]
	v_pk_fma_f32 v[122:123], v[130:131], v[138:139], v[122:123] op_sel_hi:[0,1,1]
	v_pk_fma_f32 v[120:121], v[130:131], v[140:141], v[120:121] op_sel_hi:[0,1,1]
	v_cvt_scalef32_pk_f32_fp4 v[134:135], v143, 1.0
	v_cvt_scalef32_pk_f32_fp4 v[136:137], v143, 1.0 op_sel:[1,0,0]
	v_cvt_scalef32_pk_f32_fp4 v[138:139], v143, 1.0 op_sel:[0,1,0]
	v_cvt_scalef32_pk_f32_fp4 v[140:141], v143, 1.0 op_sel:[1,1,0]
	v_pk_fma_f32 v[118:119], v[130:131], v[134:135], v[118:119] op_sel_hi:[0,1,1]
	v_pk_fma_f32 v[116:117], v[130:131], v[136:137], v[116:117] op_sel_hi:[0,1,1]
	v_pk_fma_f32 v[114:115], v[130:131], v[138:139], v[114:115] op_sel_hi:[0,1,1]
	v_pk_fma_f32 v[112:113], v[130:131], v[140:141], v[112:113] op_sel_hi:[0,1,1]
	v_cvt_scalef32_pk_f32_fp4 v[134:135], v144, 1.0
	v_cvt_scalef32_pk_f32_fp4 v[136:137], v144, 1.0 op_sel:[1,0,0]
	v_cvt_scalef32_pk_f32_fp4 v[138:139], v144, 1.0 op_sel:[0,1,0]
	v_cvt_scalef32_pk_f32_fp4 v[140:141], v144, 1.0 op_sel:[1,1,0]
	v_pk_fma_f32 v[80:81], v[130:131], v[134:135], v[80:81] op_sel_hi:[0,1,1]
	v_pk_fma_f32 v[78:79], v[130:131], v[136:137], v[78:79] op_sel_hi:[0,1,1]
	v_pk_fma_f32 v[76:77], v[130:131], v[138:139], v[76:77] op_sel_hi:[0,1,1]
	v_pk_fma_f32 v[74:75], v[130:131], v[140:141], v[74:75] op_sel_hi:[0,1,1]
	v_cvt_scalef32_pk_f32_fp4 v[134:135], v145, 1.0
	v_cvt_scalef32_pk_f32_fp4 v[136:137], v145, 1.0 op_sel:[1,0,0]
	v_cvt_scalef32_pk_f32_fp4 v[138:139], v145, 1.0 op_sel:[0,1,0]
	v_cvt_scalef32_pk_f32_fp4 v[140:141], v145, 1.0 op_sel:[1,1,0]
	v_pk_fma_f32 v[72:73], v[130:131], v[134:135], v[72:73] op_sel_hi:[0,1,1]
	v_pk_fma_f32 v[70:71], v[130:131], v[136:137], v[70:71] op_sel_hi:[0,1,1]
	v_pk_fma_f32 v[68:69], v[130:131], v[138:139], v[68:69] op_sel_hi:[0,1,1]
	v_pk_fma_f32 v[66:67], v[130:131], v[140:141], v[66:67] op_sel_hi:[0,1,1]
	s_waitcnt vmcnt(14)
	v_cvt_scalef32_pk_f32_fp4 v[134:135], v146, 1.0
	v_cvt_scalef32_pk_f32_fp4 v[136:137], v146, 1.0 op_sel:[1,0,0]
	v_cvt_scalef32_pk_f32_fp4 v[138:139], v146, 1.0 op_sel:[0,1,0]
	v_cvt_scalef32_pk_f32_fp4 v[140:141], v146, 1.0 op_sel:[1,1,0]
	v_pk_fma_f32 v[34:35], v[130:131], v[134:135], v[34:35] op_sel_hi:[0,1,1]
	v_pk_fma_f32 v[36:37], v[130:131], v[136:137], v[36:37] op_sel_hi:[0,1,1]
	v_pk_fma_f32 v[38:39], v[130:131], v[138:139], v[38:39] op_sel_hi:[0,1,1]
	v_pk_fma_f32 v[40:41], v[130:131], v[140:141], v[40:41] op_sel_hi:[0,1,1]
	v_cvt_scalef32_pk_f32_fp4 v[134:135], v147, 1.0
	v_cvt_scalef32_pk_f32_fp4 v[136:137], v147, 1.0 op_sel:[1,0,0]
	v_cvt_scalef32_pk_f32_fp4 v[138:139], v147, 1.0 op_sel:[0,1,0]
	v_cvt_scalef32_pk_f32_fp4 v[140:141], v147, 1.0 op_sel:[1,1,0]
	v_pk_fma_f32 v[42:43], v[130:131], v[134:135], v[42:43] op_sel_hi:[0,1,1]
	v_pk_fma_f32 v[44:45], v[130:131], v[136:137], v[44:45] op_sel_hi:[0,1,1]
	v_pk_fma_f32 v[46:47], v[130:131], v[138:139], v[46:47] op_sel_hi:[0,1,1]
	v_pk_fma_f32 v[48:49], v[130:131], v[140:141], v[48:49] op_sel_hi:[0,1,1]
	v_cvt_scalef32_pk_f32_fp4 v[134:135], v148, 1.0
	v_cvt_scalef32_pk_f32_fp4 v[136:137], v148, 1.0 op_sel:[1,0,0]
	v_cvt_scalef32_pk_f32_fp4 v[138:139], v148, 1.0 op_sel:[0,1,0]
	v_cvt_scalef32_pk_f32_fp4 v[140:141], v148, 1.0 op_sel:[1,1,0]
	v_pk_fma_f32 v[50:51], v[130:131], v[134:135], v[50:51] op_sel_hi:[0,1,1]
	v_pk_fma_f32 v[52:53], v[130:131], v[136:137], v[52:53] op_sel_hi:[0,1,1]
	v_pk_fma_f32 v[54:55], v[130:131], v[138:139], v[54:55] op_sel_hi:[0,1,1]
	v_pk_fma_f32 v[56:57], v[130:131], v[140:141], v[56:57] op_sel_hi:[0,1,1]
	v_cvt_scalef32_pk_f32_fp4 v[134:135], v149, 1.0
	v_cvt_scalef32_pk_f32_fp4 v[136:137], v149, 1.0 op_sel:[1,0,0]
	v_cvt_scalef32_pk_f32_fp4 v[138:139], v149, 1.0 op_sel:[0,1,0]
	v_cvt_scalef32_pk_f32_fp4 v[140:141], v149, 1.0 op_sel:[1,1,0]
	v_pk_fma_f32 v[58:59], v[130:131], v[134:135], v[58:59] op_sel_hi:[0,1,1]
	v_pk_fma_f32 v[60:61], v[130:131], v[136:137], v[60:61] op_sel_hi:[0,1,1]
	v_pk_fma_f32 v[62:63], v[130:131], v[138:139], v[62:63] op_sel_hi:[0,1,1]
	v_pk_fma_f32 v[64:65], v[130:131], v[140:141], v[64:65] op_sel_hi:[0,1,1]
	v_mad_u64_u32 v[248:249], vcc, v227, s0, v[86:87]
	global_load_dwordx4 v[142:145], v[248:249], off
	global_load_dwordx4 v[146:149], v[248:249], off offset:256
	ds_read_b32 v250, v131 offset:80
	ds_read_b32 v130, v132 offset:80
	s_waitcnt vmcnt(15)
	v_cvt_scalef32_pk_f32_fp4 v[134:135], v150, 1.0
	v_cvt_scalef32_pk_f32_fp4 v[136:137], v150, 1.0 op_sel:[1,0,0]
	v_cvt_scalef32_pk_f32_fp4 v[138:139], v150, 1.0 op_sel:[0,1,0]
	v_cvt_scalef32_pk_f32_fp4 v[140:141], v150, 1.0 op_sel:[1,1,0]
	s_waitcnt lgkmcnt(0)
	v_pk_fma_f32 v[128:129], v[130:131], v[134:135], v[128:129] op_sel_hi:[0,1,1]
	v_pk_fma_f32 v[126:127], v[130:131], v[136:137], v[126:127] op_sel_hi:[0,1,1]
	v_pk_fma_f32 v[122:123], v[130:131], v[138:139], v[122:123] op_sel_hi:[0,1,1]
	v_pk_fma_f32 v[120:121], v[130:131], v[140:141], v[120:121] op_sel_hi:[0,1,1]
	v_cvt_scalef32_pk_f32_fp4 v[134:135], v151, 1.0
	v_cvt_scalef32_pk_f32_fp4 v[136:137], v151, 1.0 op_sel:[1,0,0]
	v_cvt_scalef32_pk_f32_fp4 v[138:139], v151, 1.0 op_sel:[0,1,0]
	v_cvt_scalef32_pk_f32_fp4 v[140:141], v151, 1.0 op_sel:[1,1,0]
	v_pk_fma_f32 v[118:119], v[130:131], v[134:135], v[118:119] op_sel_hi:[0,1,1]
	v_pk_fma_f32 v[116:117], v[130:131], v[136:137], v[116:117] op_sel_hi:[0,1,1]
	v_pk_fma_f32 v[114:115], v[130:131], v[138:139], v[114:115] op_sel_hi:[0,1,1]
	v_pk_fma_f32 v[112:113], v[130:131], v[140:141], v[112:113] op_sel_hi:[0,1,1]
	v_cvt_scalef32_pk_f32_fp4 v[134:135], v152, 1.0
	v_cvt_scalef32_pk_f32_fp4 v[136:137], v152, 1.0 op_sel:[1,0,0]
	v_cvt_scalef32_pk_f32_fp4 v[138:139], v152, 1.0 op_sel:[0,1,0]
	v_cvt_scalef32_pk_f32_fp4 v[140:141], v152, 1.0 op_sel:[1,1,0]
	v_pk_fma_f32 v[80:81], v[130:131], v[134:135], v[80:81] op_sel_hi:[0,1,1]
	v_pk_fma_f32 v[78:79], v[130:131], v[136:137], v[78:79] op_sel_hi:[0,1,1]
	v_pk_fma_f32 v[76:77], v[130:131], v[138:139], v[76:77] op_sel_hi:[0,1,1]
	v_pk_fma_f32 v[74:75], v[130:131], v[140:141], v[74:75] op_sel_hi:[0,1,1]
	v_cvt_scalef32_pk_f32_fp4 v[134:135], v153, 1.0
	v_cvt_scalef32_pk_f32_fp4 v[136:137], v153, 1.0 op_sel:[1,0,0]
	v_cvt_scalef32_pk_f32_fp4 v[138:139], v153, 1.0 op_sel:[0,1,0]
	v_cvt_scalef32_pk_f32_fp4 v[140:141], v153, 1.0 op_sel:[1,1,0]
	v_pk_fma_f32 v[72:73], v[130:131], v[134:135], v[72:73] op_sel_hi:[0,1,1]
	v_pk_fma_f32 v[70:71], v[130:131], v[136:137], v[70:71] op_sel_hi:[0,1,1]
	v_pk_fma_f32 v[68:69], v[130:131], v[138:139], v[68:69] op_sel_hi:[0,1,1]
	v_pk_fma_f32 v[66:67], v[130:131], v[140:141], v[66:67] op_sel_hi:[0,1,1]
	s_waitcnt vmcnt(14)
	v_cvt_scalef32_pk_f32_fp4 v[134:135], v232, 1.0
	v_cvt_scalef32_pk_f32_fp4 v[136:137], v232, 1.0 op_sel:[1,0,0]
	v_cvt_scalef32_pk_f32_fp4 v[138:139], v232, 1.0 op_sel:[0,1,0]
	v_cvt_scalef32_pk_f32_fp4 v[140:141], v232, 1.0 op_sel:[1,1,0]
	v_pk_fma_f32 v[34:35], v[130:131], v[134:135], v[34:35] op_sel_hi:[0,1,1]
	v_pk_fma_f32 v[36:37], v[130:131], v[136:137], v[36:37] op_sel_hi:[0,1,1]
	v_pk_fma_f32 v[38:39], v[130:131], v[138:139], v[38:39] op_sel_hi:[0,1,1]
	v_pk_fma_f32 v[40:41], v[130:131], v[140:141], v[40:41] op_sel_hi:[0,1,1]
	v_cvt_scalef32_pk_f32_fp4 v[134:135], v233, 1.0
	v_cvt_scalef32_pk_f32_fp4 v[136:137], v233, 1.0 op_sel:[1,0,0]
	v_cvt_scalef32_pk_f32_fp4 v[138:139], v233, 1.0 op_sel:[0,1,0]
	v_cvt_scalef32_pk_f32_fp4 v[140:141], v233, 1.0 op_sel:[1,1,0]
	v_pk_fma_f32 v[42:43], v[130:131], v[134:135], v[42:43] op_sel_hi:[0,1,1]
	v_pk_fma_f32 v[44:45], v[130:131], v[136:137], v[44:45] op_sel_hi:[0,1,1]
	v_pk_fma_f32 v[46:47], v[130:131], v[138:139], v[46:47] op_sel_hi:[0,1,1]
	v_pk_fma_f32 v[48:49], v[130:131], v[140:141], v[48:49] op_sel_hi:[0,1,1]
	v_cvt_scalef32_pk_f32_fp4 v[134:135], v234, 1.0
	v_cvt_scalef32_pk_f32_fp4 v[136:137], v234, 1.0 op_sel:[1,0,0]
	v_cvt_scalef32_pk_f32_fp4 v[138:139], v234, 1.0 op_sel:[0,1,0]
	v_cvt_scalef32_pk_f32_fp4 v[140:141], v234, 1.0 op_sel:[1,1,0]
	v_pk_fma_f32 v[50:51], v[130:131], v[134:135], v[50:51] op_sel_hi:[0,1,1]
	v_pk_fma_f32 v[52:53], v[130:131], v[136:137], v[52:53] op_sel_hi:[0,1,1]
	v_pk_fma_f32 v[54:55], v[130:131], v[138:139], v[54:55] op_sel_hi:[0,1,1]
	v_pk_fma_f32 v[56:57], v[130:131], v[140:141], v[56:57] op_sel_hi:[0,1,1]
	v_cvt_scalef32_pk_f32_fp4 v[134:135], v235, 1.0
	v_cvt_scalef32_pk_f32_fp4 v[136:137], v235, 1.0 op_sel:[1,0,0]
	v_cvt_scalef32_pk_f32_fp4 v[138:139], v235, 1.0 op_sel:[0,1,0]
	v_cvt_scalef32_pk_f32_fp4 v[140:141], v235, 1.0 op_sel:[1,1,0]
	v_pk_fma_f32 v[58:59], v[130:131], v[134:135], v[58:59] op_sel_hi:[0,1,1]
	v_pk_fma_f32 v[60:61], v[130:131], v[136:137], v[60:61] op_sel_hi:[0,1,1]
	v_pk_fma_f32 v[62:63], v[130:131], v[138:139], v[62:63] op_sel_hi:[0,1,1]
	v_pk_fma_f32 v[64:65], v[130:131], v[140:141], v[64:65] op_sel_hi:[0,1,1]
	v_mad_u64_u32 v[248:249], vcc, v250, s0, v[86:87]
	global_load_dwordx4 v[150:153], v[248:249], off
	global_load_dwordx4 v[232:235], v[248:249], off offset:256
	ds_read_b32 v227, v131 offset:96
	ds_read_b32 v130, v132 offset:96
	s_waitcnt vmcnt(15)
	v_cvt_scalef32_pk_f32_fp4 v[134:135], v236, 1.0
	v_cvt_scalef32_pk_f32_fp4 v[136:137], v236, 1.0 op_sel:[1,0,0]
	v_cvt_scalef32_pk_f32_fp4 v[138:139], v236, 1.0 op_sel:[0,1,0]
	v_cvt_scalef32_pk_f32_fp4 v[140:141], v236, 1.0 op_sel:[1,1,0]
	s_waitcnt lgkmcnt(0)
	v_pk_fma_f32 v[128:129], v[130:131], v[134:135], v[128:129] op_sel_hi:[0,1,1]
	v_pk_fma_f32 v[126:127], v[130:131], v[136:137], v[126:127] op_sel_hi:[0,1,1]
	v_pk_fma_f32 v[122:123], v[130:131], v[138:139], v[122:123] op_sel_hi:[0,1,1]
	v_pk_fma_f32 v[120:121], v[130:131], v[140:141], v[120:121] op_sel_hi:[0,1,1]
	v_cvt_scalef32_pk_f32_fp4 v[134:135], v237, 1.0
	v_cvt_scalef32_pk_f32_fp4 v[136:137], v237, 1.0 op_sel:[1,0,0]
	v_cvt_scalef32_pk_f32_fp4 v[138:139], v237, 1.0 op_sel:[0,1,0]
	v_cvt_scalef32_pk_f32_fp4 v[140:141], v237, 1.0 op_sel:[1,1,0]
	v_pk_fma_f32 v[118:119], v[130:131], v[134:135], v[118:119] op_sel_hi:[0,1,1]
	v_pk_fma_f32 v[116:117], v[130:131], v[136:137], v[116:117] op_sel_hi:[0,1,1]
	v_pk_fma_f32 v[114:115], v[130:131], v[138:139], v[114:115] op_sel_hi:[0,1,1]
	v_pk_fma_f32 v[112:113], v[130:131], v[140:141], v[112:113] op_sel_hi:[0,1,1]
	v_cvt_scalef32_pk_f32_fp4 v[134:135], v238, 1.0
	v_cvt_scalef32_pk_f32_fp4 v[136:137], v238, 1.0 op_sel:[1,0,0]
	v_cvt_scalef32_pk_f32_fp4 v[138:139], v238, 1.0 op_sel:[0,1,0]
	v_cvt_scalef32_pk_f32_fp4 v[140:141], v238, 1.0 op_sel:[1,1,0]
	v_pk_fma_f32 v[80:81], v[130:131], v[134:135], v[80:81] op_sel_hi:[0,1,1]
	v_pk_fma_f32 v[78:79], v[130:131], v[136:137], v[78:79] op_sel_hi:[0,1,1]
	v_pk_fma_f32 v[76:77], v[130:131], v[138:139], v[76:77] op_sel_hi:[0,1,1]
	v_pk_fma_f32 v[74:75], v[130:131], v[140:141], v[74:75] op_sel_hi:[0,1,1]
	v_cvt_scalef32_pk_f32_fp4 v[134:135], v239, 1.0
	v_cvt_scalef32_pk_f32_fp4 v[136:137], v239, 1.0 op_sel:[1,0,0]
	v_cvt_scalef32_pk_f32_fp4 v[138:139], v239, 1.0 op_sel:[0,1,0]
	v_cvt_scalef32_pk_f32_fp4 v[140:141], v239, 1.0 op_sel:[1,1,0]
	v_pk_fma_f32 v[72:73], v[130:131], v[134:135], v[72:73] op_sel_hi:[0,1,1]
	v_pk_fma_f32 v[70:71], v[130:131], v[136:137], v[70:71] op_sel_hi:[0,1,1]
	v_pk_fma_f32 v[68:69], v[130:131], v[138:139], v[68:69] op_sel_hi:[0,1,1]
	v_pk_fma_f32 v[66:67], v[130:131], v[140:141], v[66:67] op_sel_hi:[0,1,1]
	s_waitcnt vmcnt(14)
	v_cvt_scalef32_pk_f32_fp4 v[134:135], v240, 1.0
	v_cvt_scalef32_pk_f32_fp4 v[136:137], v240, 1.0 op_sel:[1,0,0]
	v_cvt_scalef32_pk_f32_fp4 v[138:139], v240, 1.0 op_sel:[0,1,0]
	v_cvt_scalef32_pk_f32_fp4 v[140:141], v240, 1.0 op_sel:[1,1,0]
	v_pk_fma_f32 v[34:35], v[130:131], v[134:135], v[34:35] op_sel_hi:[0,1,1]
	v_pk_fma_f32 v[36:37], v[130:131], v[136:137], v[36:37] op_sel_hi:[0,1,1]
	v_pk_fma_f32 v[38:39], v[130:131], v[138:139], v[38:39] op_sel_hi:[0,1,1]
	v_pk_fma_f32 v[40:41], v[130:131], v[140:141], v[40:41] op_sel_hi:[0,1,1]
	v_cvt_scalef32_pk_f32_fp4 v[134:135], v241, 1.0
	v_cvt_scalef32_pk_f32_fp4 v[136:137], v241, 1.0 op_sel:[1,0,0]
	v_cvt_scalef32_pk_f32_fp4 v[138:139], v241, 1.0 op_sel:[0,1,0]
	v_cvt_scalef32_pk_f32_fp4 v[140:141], v241, 1.0 op_sel:[1,1,0]
	v_pk_fma_f32 v[42:43], v[130:131], v[134:135], v[42:43] op_sel_hi:[0,1,1]
	v_pk_fma_f32 v[44:45], v[130:131], v[136:137], v[44:45] op_sel_hi:[0,1,1]
	v_pk_fma_f32 v[46:47], v[130:131], v[138:139], v[46:47] op_sel_hi:[0,1,1]
	v_pk_fma_f32 v[48:49], v[130:131], v[140:141], v[48:49] op_sel_hi:[0,1,1]
	v_cvt_scalef32_pk_f32_fp4 v[134:135], v242, 1.0
	v_cvt_scalef32_pk_f32_fp4 v[136:137], v242, 1.0 op_sel:[1,0,0]
	v_cvt_scalef32_pk_f32_fp4 v[138:139], v242, 1.0 op_sel:[0,1,0]
	v_cvt_scalef32_pk_f32_fp4 v[140:141], v242, 1.0 op_sel:[1,1,0]
	v_pk_fma_f32 v[50:51], v[130:131], v[134:135], v[50:51] op_sel_hi:[0,1,1]
	v_pk_fma_f32 v[52:53], v[130:131], v[136:137], v[52:53] op_sel_hi:[0,1,1]
	v_pk_fma_f32 v[54:55], v[130:131], v[138:139], v[54:55] op_sel_hi:[0,1,1]
	v_pk_fma_f32 v[56:57], v[130:131], v[140:141], v[56:57] op_sel_hi:[0,1,1]
	v_cvt_scalef32_pk_f32_fp4 v[134:135], v243, 1.0
	v_cvt_scalef32_pk_f32_fp4 v[136:137], v243, 1.0 op_sel:[1,0,0]
	v_cvt_scalef32_pk_f32_fp4 v[138:139], v243, 1.0 op_sel:[0,1,0]
	v_cvt_scalef32_pk_f32_fp4 v[140:141], v243, 1.0 op_sel:[1,1,0]
	v_pk_fma_f32 v[58:59], v[130:131], v[134:135], v[58:59] op_sel_hi:[0,1,1]
	v_pk_fma_f32 v[60:61], v[130:131], v[136:137], v[60:61] op_sel_hi:[0,1,1]
	v_pk_fma_f32 v[62:63], v[130:131], v[138:139], v[62:63] op_sel_hi:[0,1,1]
	v_pk_fma_f32 v[64:65], v[130:131], v[140:141], v[64:65] op_sel_hi:[0,1,1]
	v_mad_u64_u32 v[248:249], vcc, v227, s0, v[86:87]
	global_load_dwordx4 v[236:239], v[248:249], off
	global_load_dwordx4 v[240:243], v[248:249], off offset:256
	ds_read_b32 v250, v131 offset:112
	ds_read_b32 v130, v132 offset:112
	s_waitcnt vmcnt(15)
	v_cvt_scalef32_pk_f32_fp4 v[134:135], v244, 1.0
	v_cvt_scalef32_pk_f32_fp4 v[136:137], v244, 1.0 op_sel:[1,0,0]
	v_cvt_scalef32_pk_f32_fp4 v[138:139], v244, 1.0 op_sel:[0,1,0]
	v_cvt_scalef32_pk_f32_fp4 v[140:141], v244, 1.0 op_sel:[1,1,0]
	s_waitcnt lgkmcnt(0)
	v_pk_fma_f32 v[128:129], v[130:131], v[134:135], v[128:129] op_sel_hi:[0,1,1]
	v_pk_fma_f32 v[126:127], v[130:131], v[136:137], v[126:127] op_sel_hi:[0,1,1]
	v_pk_fma_f32 v[122:123], v[130:131], v[138:139], v[122:123] op_sel_hi:[0,1,1]
	v_pk_fma_f32 v[120:121], v[130:131], v[140:141], v[120:121] op_sel_hi:[0,1,1]
	v_cvt_scalef32_pk_f32_fp4 v[134:135], v245, 1.0
	v_cvt_scalef32_pk_f32_fp4 v[136:137], v245, 1.0 op_sel:[1,0,0]
	v_cvt_scalef32_pk_f32_fp4 v[138:139], v245, 1.0 op_sel:[0,1,0]
	v_cvt_scalef32_pk_f32_fp4 v[140:141], v245, 1.0 op_sel:[1,1,0]
	v_pk_fma_f32 v[118:119], v[130:131], v[134:135], v[118:119] op_sel_hi:[0,1,1]
	v_pk_fma_f32 v[116:117], v[130:131], v[136:137], v[116:117] op_sel_hi:[0,1,1]
	v_pk_fma_f32 v[114:115], v[130:131], v[138:139], v[114:115] op_sel_hi:[0,1,1]
	v_pk_fma_f32 v[112:113], v[130:131], v[140:141], v[112:113] op_sel_hi:[0,1,1]
	v_cvt_scalef32_pk_f32_fp4 v[134:135], v246, 1.0
	v_cvt_scalef32_pk_f32_fp4 v[136:137], v246, 1.0 op_sel:[1,0,0]
	v_cvt_scalef32_pk_f32_fp4 v[138:139], v246, 1.0 op_sel:[0,1,0]
	v_cvt_scalef32_pk_f32_fp4 v[140:141], v246, 1.0 op_sel:[1,1,0]
	v_pk_fma_f32 v[80:81], v[130:131], v[134:135], v[80:81] op_sel_hi:[0,1,1]
	v_pk_fma_f32 v[78:79], v[130:131], v[136:137], v[78:79] op_sel_hi:[0,1,1]
	v_pk_fma_f32 v[76:77], v[130:131], v[138:139], v[76:77] op_sel_hi:[0,1,1]
	v_pk_fma_f32 v[74:75], v[130:131], v[140:141], v[74:75] op_sel_hi:[0,1,1]
	v_cvt_scalef32_pk_f32_fp4 v[134:135], v247, 1.0
	v_cvt_scalef32_pk_f32_fp4 v[136:137], v247, 1.0 op_sel:[1,0,0]
	v_cvt_scalef32_pk_f32_fp4 v[138:139], v247, 1.0 op_sel:[0,1,0]
	v_cvt_scalef32_pk_f32_fp4 v[140:141], v247, 1.0 op_sel:[1,1,0]
	v_pk_fma_f32 v[72:73], v[130:131], v[134:135], v[72:73] op_sel_hi:[0,1,1]
	v_pk_fma_f32 v[70:71], v[130:131], v[136:137], v[70:71] op_sel_hi:[0,1,1]
	v_pk_fma_f32 v[68:69], v[130:131], v[138:139], v[68:69] op_sel_hi:[0,1,1]
	v_pk_fma_f32 v[66:67], v[130:131], v[140:141], v[66:67] op_sel_hi:[0,1,1]
	s_waitcnt vmcnt(14)
	v_cvt_scalef32_pk_f32_fp4 v[134:135], v228, 1.0
	v_cvt_scalef32_pk_f32_fp4 v[136:137], v228, 1.0 op_sel:[1,0,0]
	v_cvt_scalef32_pk_f32_fp4 v[138:139], v228, 1.0 op_sel:[0,1,0]
	v_cvt_scalef32_pk_f32_fp4 v[140:141], v228, 1.0 op_sel:[1,1,0]
	v_pk_fma_f32 v[34:35], v[130:131], v[134:135], v[34:35] op_sel_hi:[0,1,1]
	v_pk_fma_f32 v[36:37], v[130:131], v[136:137], v[36:37] op_sel_hi:[0,1,1]
	v_pk_fma_f32 v[38:39], v[130:131], v[138:139], v[38:39] op_sel_hi:[0,1,1]
	v_pk_fma_f32 v[40:41], v[130:131], v[140:141], v[40:41] op_sel_hi:[0,1,1]
	v_cvt_scalef32_pk_f32_fp4 v[134:135], v229, 1.0
	v_cvt_scalef32_pk_f32_fp4 v[136:137], v229, 1.0 op_sel:[1,0,0]
	v_cvt_scalef32_pk_f32_fp4 v[138:139], v229, 1.0 op_sel:[0,1,0]
	v_cvt_scalef32_pk_f32_fp4 v[140:141], v229, 1.0 op_sel:[1,1,0]
	v_pk_fma_f32 v[42:43], v[130:131], v[134:135], v[42:43] op_sel_hi:[0,1,1]
	v_pk_fma_f32 v[44:45], v[130:131], v[136:137], v[44:45] op_sel_hi:[0,1,1]
	v_pk_fma_f32 v[46:47], v[130:131], v[138:139], v[46:47] op_sel_hi:[0,1,1]
	v_pk_fma_f32 v[48:49], v[130:131], v[140:141], v[48:49] op_sel_hi:[0,1,1]
	v_cvt_scalef32_pk_f32_fp4 v[134:135], v230, 1.0
	v_cvt_scalef32_pk_f32_fp4 v[136:137], v230, 1.0 op_sel:[1,0,0]
	v_cvt_scalef32_pk_f32_fp4 v[138:139], v230, 1.0 op_sel:[0,1,0]
	v_cvt_scalef32_pk_f32_fp4 v[140:141], v230, 1.0 op_sel:[1,1,0]
	v_pk_fma_f32 v[50:51], v[130:131], v[134:135], v[50:51] op_sel_hi:[0,1,1]
	v_pk_fma_f32 v[52:53], v[130:131], v[136:137], v[52:53] op_sel_hi:[0,1,1]
	v_pk_fma_f32 v[54:55], v[130:131], v[138:139], v[54:55] op_sel_hi:[0,1,1]
	v_pk_fma_f32 v[56:57], v[130:131], v[140:141], v[56:57] op_sel_hi:[0,1,1]
	v_cvt_scalef32_pk_f32_fp4 v[134:135], v231, 1.0
	v_cvt_scalef32_pk_f32_fp4 v[136:137], v231, 1.0 op_sel:[1,0,0]
	v_cvt_scalef32_pk_f32_fp4 v[138:139], v231, 1.0 op_sel:[0,1,0]
	v_cvt_scalef32_pk_f32_fp4 v[140:141], v231, 1.0 op_sel:[1,1,0]
	v_pk_fma_f32 v[58:59], v[130:131], v[134:135], v[58:59] op_sel_hi:[0,1,1]
	v_pk_fma_f32 v[60:61], v[130:131], v[136:137], v[60:61] op_sel_hi:[0,1,1]
	v_pk_fma_f32 v[62:63], v[130:131], v[138:139], v[62:63] op_sel_hi:[0,1,1]
	v_pk_fma_f32 v[64:65], v[130:131], v[140:141], v[64:65] op_sel_hi:[0,1,1]
	s_add_i32 s2, s2, 8
	v_add_u32_e32 v131, 0x80, v131
	v_add_u32_e32 v132, 0x80, v132
	s_cmp_lt_u32 s2, 24
	s_cbranch_scc1 .Lpv_loop
	v_mad_u64_u32 v[248:249], vcc, v250, s0, v[86:87]
	global_load_dwordx4 v[244:247], v[248:249], off
	global_load_dwordx4 v[228:231], v[248:249], off offset:256
	ds_read_b32 v130, v132 offset:0
	s_waitcnt vmcnt(15)
	v_cvt_scalef32_pk_f32_fp4 v[134:135], v10, 1.0
	v_cvt_scalef32_pk_f32_fp4 v[136:137], v10, 1.0 op_sel:[1,0,0]
	v_cvt_scalef32_pk_f32_fp4 v[138:139], v10, 1.0 op_sel:[0,1,0]
	v_cvt_scalef32_pk_f32_fp4 v[140:141], v10, 1.0 op_sel:[1,1,0]
	s_waitcnt lgkmcnt(0)
	v_pk_fma_f32 v[128:129], v[130:131], v[134:135], v[128:129] op_sel_hi:[0,1,1]
	v_pk_fma_f32 v[126:127], v[130:131], v[136:137], v[126:127] op_sel_hi:[0,1,1]
	v_pk_fma_f32 v[122:123], v[130:131], v[138:139], v[122:123] op_sel_hi:[0,1,1]
	v_pk_fma_f32 v[120:121], v[130:131], v[140:141], v[120:121] op_sel_hi:[0,1,1]
	v_cvt_scalef32_pk_f32_fp4 v[134:135], v11, 1.0
	v_cvt_scalef32_pk_f32_fp4 v[136:137], v11, 1.0 op_sel:[1,0,0]
	v_cvt_scalef32_pk_f32_fp4 v[138:139], v11, 1.0 op_sel:[0,1,0]
	v_cvt_scalef32_pk_f32_fp4 v[140:141], v11, 1.0 op_sel:[1,1,0]
	v_pk_fma_f32 v[118:119], v[130:131], v[134:135], v[118:119] op_sel_hi:[0,1,1]
	v_pk_fma_f32 v[116:117], v[130:131], v[136:137], v[116:117] op_sel_hi:[0,1,1]
	v_pk_fma_f32 v[114:115], v[130:131], v[138:139], v[114:115] op_sel_hi:[0,1,1]
	v_pk_fma_f32 v[112:113], v[130:131], v[140:141], v[112:113] op_sel_hi:[0,1,1]
	v_cvt_scalef32_pk_f32_fp4 v[134:135], v12, 1.0
	v_cvt_scalef32_pk_f32_fp4 v[136:137], v12, 1.0 op_sel:[1,0,0]
	v_cvt_scalef32_pk_f32_fp4 v[138:139], v12, 1.0 op_sel:[0,1,0]
	v_cvt_scalef32_pk_f32_fp4 v[140:141], v12, 1.0 op_sel:[1,1,0]
	v_pk_fma_f32 v[80:81], v[130:131], v[134:135], v[80:81] op_sel_hi:[0,1,1]
	v_pk_fma_f32 v[78:79], v[130:131], v[136:137], v[78:79] op_sel_hi:[0,1,1]
	v_pk_fma_f32 v[76:77], v[130:131], v[138:139], v[76:77] op_sel_hi:[0,1,1]
	v_pk_fma_f32 v[74:75], v[130:131], v[140:141], v[74:75] op_sel_hi:[0,1,1]
	v_cvt_scalef32_pk_f32_fp4 v[134:135], v13, 1.0
	v_cvt_scalef32_pk_f32_fp4 v[136:137], v13, 1.0 op_sel:[1,0,0]
	v_cvt_scalef32_pk_f32_fp4 v[138:139], v13, 1.0 op_sel:[0,1,0]
	v_cvt_scalef32_pk_f32_fp4 v[140:141], v13, 1.0 op_sel:[1,1,0]
	v_pk_fma_f32 v[72:73], v[130:131], v[134:135], v[72:73] op_sel_hi:[0,1,1]
	v_pk_fma_f32 v[70:71], v[130:131], v[136:137], v[70:71] op_sel_hi:[0,1,1]
	v_pk_fma_f32 v[68:69], v[130:131], v[138:139], v[68:69] op_sel_hi:[0,1,1]
	v_pk_fma_f32 v[66:67], v[130:131], v[140:141], v[66:67] op_sel_hi:[0,1,1]
	s_waitcnt vmcnt(14)
	v_cvt_scalef32_pk_f32_fp4 v[134:135], v2, 1.0
	v_cvt_scalef32_pk_f32_fp4 v[136:137], v2, 1.0 op_sel:[1,0,0]
	v_cvt_scalef32_pk_f32_fp4 v[138:139], v2, 1.0 op_sel:[0,1,0]
	v_cvt_scalef32_pk_f32_fp4 v[140:141], v2, 1.0 op_sel:[1,1,0]
	v_pk_fma_f32 v[34:35], v[130:131], v[134:135], v[34:35] op_sel_hi:[0,1,1]
	v_pk_fma_f32 v[36:37], v[130:131], v[136:137], v[36:37] op_sel_hi:[0,1,1]
	v_pk_fma_f32 v[38:39], v[130:131], v[138:139], v[38:39] op_sel_hi:[0,1,1]
	v_pk_fma_f32 v[40:41], v[130:131], v[140:141], v[40:41] op_sel_hi:[0,1,1]
	v_cvt_scalef32_pk_f32_fp4 v[134:135], v3, 1.0
	v_cvt_scalef32_pk_f32_fp4 v[136:137], v3, 1.0 op_sel:[1,0,0]
	v_cvt_scalef32_pk_f32_fp4 v[138:139], v3, 1.0 op_sel:[0,1,0]
	v_cvt_scalef32_pk_f32_fp4 v[140:141], v3, 1.0 op_sel:[1,1,0]
	v_pk_fma_f32 v[42:43], v[130:131], v[134:135], v[42:43] op_sel_hi:[0,1,1]
	v_pk_fma_f32 v[44:45], v[130:131], v[136:137], v[44:45] op_sel_hi:[0,1,1]
	v_pk_fma_f32 v[46:47], v[130:131], v[138:139], v[46:47] op_sel_hi:[0,1,1]
	v_pk_fma_f32 v[48:49], v[130:131], v[140:141], v[48:49] op_sel_hi:[0,1,1]
	v_cvt_scalef32_pk_f32_fp4 v[134:135], v4, 1.0
	v_cvt_scalef32_pk_f32_fp4 v[136:137], v4, 1.0 op_sel:[1,0,0]
	v_cvt_scalef32_pk_f32_fp4 v[138:139], v4, 1.0 op_sel:[0,1,0]
	v_cvt_scalef32_pk_f32_fp4 v[140:141], v4, 1.0 op_sel:[1,1,0]
	v_pk_fma_f32 v[50:51], v[130:131], v[134:135], v[50:51] op_sel_hi:[0,1,1]
	v_pk_fma_f32 v[52:53], v[130:131], v[136:137], v[52:53] op_sel_hi:[0,1,1]
	v_pk_fma_f32 v[54:55], v[130:131], v[138:139], v[54:55] op_sel_hi:[0,1,1]
	v_pk_fma_f32 v[56:57], v[130:131], v[140:141], v[56:57] op_sel_hi:[0,1,1]
	v_cvt_scalef32_pk_f32_fp4 v[134:135], v5, 1.0
	v_cvt_scalef32_pk_f32_fp4 v[136:137], v5, 1.0 op_sel:[1,0,0]
	v_cvt_scalef32_pk_f32_fp4 v[138:139], v5, 1.0 op_sel:[0,1,0]
	v_cvt_scalef32_pk_f32_fp4 v[140:141], v5, 1.0 op_sel:[1,1,0]
	v_pk_fma_f32 v[58:59], v[130:131], v[134:135], v[58:59] op_sel_hi:[0,1,1]
	v_pk_fma_f32 v[60:61], v[130:131], v[136:137], v[60:61] op_sel_hi:[0,1,1]
	v_pk_fma_f32 v[62:63], v[130:131], v[138:139], v[62:63] op_sel_hi:[0,1,1]
	v_pk_fma_f32 v[64:65], v[130:131], v[140:141], v[64:65] op_sel_hi:[0,1,1]
	ds_read_b32 v130, v132 offset:16
	s_waitcnt vmcnt(13)
	v_cvt_scalef32_pk_f32_fp4 v[134:135], v14, 1.0
	v_cvt_scalef32_pk_f32_fp4 v[136:137], v14, 1.0 op_sel:[1,0,0]
	v_cvt_scalef32_pk_f32_fp4 v[138:139], v14, 1.0 op_sel:[0,1,0]
	v_cvt_scalef32_pk_f32_fp4 v[140:141], v14, 1.0 op_sel:[1,1,0]
	s_waitcnt lgkmcnt(0)
	v_pk_fma_f32 v[128:129], v[130:131], v[134:135], v[128:129] op_sel_hi:[0,1,1]
	v_pk_fma_f32 v[126:127], v[130:131], v[136:137], v[126:127] op_sel_hi:[0,1,1]
	v_pk_fma_f32 v[122:123], v[130:131], v[138:139], v[122:123] op_sel_hi:[0,1,1]
	v_pk_fma_f32 v[120:121], v[130:131], v[140:141], v[120:121] op_sel_hi:[0,1,1]
	v_cvt_scalef32_pk_f32_fp4 v[134:135], v15, 1.0
	v_cvt_scalef32_pk_f32_fp4 v[136:137], v15, 1.0 op_sel:[1,0,0]
	v_cvt_scalef32_pk_f32_fp4 v[138:139], v15, 1.0 op_sel:[0,1,0]
	v_cvt_scalef32_pk_f32_fp4 v[140:141], v15, 1.0 op_sel:[1,1,0]
	v_pk_fma_f32 v[118:119], v[130:131], v[134:135], v[118:119] op_sel_hi:[0,1,1]
	v_pk_fma_f32 v[116:117], v[130:131], v[136:137], v[116:117] op_sel_hi:[0,1,1]
	v_pk_fma_f32 v[114:115], v[130:131], v[138:139], v[114:115] op_sel_hi:[0,1,1]
	v_pk_fma_f32 v[112:113], v[130:131], v[140:141], v[112:113] op_sel_hi:[0,1,1]
	v_cvt_scalef32_pk_f32_fp4 v[134:135], v16, 1.0
	v_cvt_scalef32_pk_f32_fp4 v[136:137], v16, 1.0 op_sel:[1,0,0]
	v_cvt_scalef32_pk_f32_fp4 v[138:139], v16, 1.0 op_sel:[0,1,0]
	v_cvt_scalef32_pk_f32_fp4 v[140:141], v16, 1.0 op_sel:[1,1,0]
	v_pk_fma_f32 v[80:81], v[130:131], v[134:135], v[80:81] op_sel_hi:[0,1,1]
	v_pk_fma_f32 v[78:79], v[130:131], v[136:137], v[78:79] op_sel_hi:[0,1,1]
	v_pk_fma_f32 v[76:77], v[130:131], v[138:139], v[76:77] op_sel_hi:[0,1,1]
	v_pk_fma_f32 v[74:75], v[130:131], v[140:141], v[74:75] op_sel_hi:[0,1,1]
	v_cvt_scalef32_pk_f32_fp4 v[134:135], v17, 1.0
	v_cvt_scalef32_pk_f32_fp4 v[136:137], v17, 1.0 op_sel:[1,0,0]
	v_cvt_scalef32_pk_f32_fp4 v[138:139], v17, 1.0 op_sel:[0,1,0]
	v_cvt_scalef32_pk_f32_fp4 v[140:141], v17, 1.0 op_sel:[1,1,0]
	v_pk_fma_f32 v[72:73], v[130:131], v[134:135], v[72:73] op_sel_hi:[0,1,1]
	v_pk_fma_f32 v[70:71], v[130:131], v[136:137], v[70:71] op_sel_hi:[0,1,1]
	v_pk_fma_f32 v[68:69], v[130:131], v[138:139], v[68:69] op_sel_hi:[0,1,1]
	v_pk_fma_f32 v[66:67], v[130:131], v[140:141], v[66:67] op_sel_hi:[0,1,1]
	s_waitcnt vmcnt(12)
	v_cvt_scalef32_pk_f32_fp4 v[134:135], v6, 1.0
	v_cvt_scalef32_pk_f32_fp4 v[136:137], v6, 1.0 op_sel:[1,0,0]
	v_cvt_scalef32_pk_f32_fp4 v[138:139], v6, 1.0 op_sel:[0,1,0]
	v_cvt_scalef32_pk_f32_fp4 v[140:141], v6, 1.0 op_sel:[1,1,0]
	v_pk_fma_f32 v[34:35], v[130:131], v[134:135], v[34:35] op_sel_hi:[0,1,1]
	v_pk_fma_f32 v[36:37], v[130:131], v[136:137], v[36:37] op_sel_hi:[0,1,1]
	v_pk_fma_f32 v[38:39], v[130:131], v[138:139], v[38:39] op_sel_hi:[0,1,1]
	v_pk_fma_f32 v[40:41], v[130:131], v[140:141], v[40:41] op_sel_hi:[0,1,1]
	v_cvt_scalef32_pk_f32_fp4 v[134:135], v7, 1.0
	v_cvt_scalef32_pk_f32_fp4 v[136:137], v7, 1.0 op_sel:[1,0,0]
	v_cvt_scalef32_pk_f32_fp4 v[138:139], v7, 1.0 op_sel:[0,1,0]
	v_cvt_scalef32_pk_f32_fp4 v[140:141], v7, 1.0 op_sel:[1,1,0]
	v_pk_fma_f32 v[42:43], v[130:131], v[134:135], v[42:43] op_sel_hi:[0,1,1]
	v_pk_fma_f32 v[44:45], v[130:131], v[136:137], v[44:45] op_sel_hi:[0,1,1]
	v_pk_fma_f32 v[46:47], v[130:131], v[138:139], v[46:47] op_sel_hi:[0,1,1]
	v_pk_fma_f32 v[48:49], v[130:131], v[140:141], v[48:49] op_sel_hi:[0,1,1]
	v_cvt_scalef32_pk_f32_fp4 v[134:135], v8, 1.0
	v_cvt_scalef32_pk_f32_fp4 v[136:137], v8, 1.0 op_sel:[1,0,0]
	v_cvt_scalef32_pk_f32_fp4 v[138:139], v8, 1.0 op_sel:[0,1,0]
	v_cvt_scalef32_pk_f32_fp4 v[140:141], v8, 1.0 op_sel:[1,1,0]
	v_pk_fma_f32 v[50:51], v[130:131], v[134:135], v[50:51] op_sel_hi:[0,1,1]
	v_pk_fma_f32 v[52:53], v[130:131], v[136:137], v[52:53] op_sel_hi:[0,1,1]
	v_pk_fma_f32 v[54:55], v[130:131], v[138:139], v[54:55] op_sel_hi:[0,1,1]
	v_pk_fma_f32 v[56:57], v[130:131], v[140:141], v[56:57] op_sel_hi:[0,1,1]
	v_cvt_scalef32_pk_f32_fp4 v[134:135], v9, 1.0
	v_cvt_scalef32_pk_f32_fp4 v[136:137], v9, 1.0 op_sel:[1,0,0]
	v_cvt_scalef32_pk_f32_fp4 v[138:139], v9, 1.0 op_sel:[0,1,0]
	v_cvt_scalef32_pk_f32_fp4 v[140:141], v9, 1.0 op_sel:[1,1,0]
	v_pk_fma_f32 v[58:59], v[130:131], v[134:135], v[58:59] op_sel_hi:[0,1,1]
	v_pk_fma_f32 v[60:61], v[130:131], v[136:137], v[60:61] op_sel_hi:[0,1,1]
	v_pk_fma_f32 v[62:63], v[130:131], v[138:139], v[62:63] op_sel_hi:[0,1,1]
	v_pk_fma_f32 v[64:65], v[130:131], v[140:141], v[64:65] op_sel_hi:[0,1,1]
	ds_read_b32 v130, v132 offset:32
	s_waitcnt vmcnt(11)
	v_cvt_scalef32_pk_f32_fp4 v[134:135], v22, 1.0
	v_cvt_scalef32_pk_f32_fp4 v[136:137], v22, 1.0 op_sel:[1,0,0]
	v_cvt_scalef32_pk_f32_fp4 v[138:139], v22, 1.0 op_sel:[0,1,0]
	v_cvt_scalef32_pk_f32_fp4 v[140:141], v22, 1.0 op_sel:[1,1,0]
	s_waitcnt lgkmcnt(0)
	v_pk_fma_f32 v[128:129], v[130:131], v[134:135], v[128:129] op_sel_hi:[0,1,1]
	v_pk_fma_f32 v[126:127], v[130:131], v[136:137], v[126:127] op_sel_hi:[0,1,1]
	v_pk_fma_f32 v[122:123], v[130:131], v[138:139], v[122:123] op_sel_hi:[0,1,1]
	v_pk_fma_f32 v[120:121], v[130:131], v[140:141], v[120:121] op_sel_hi:[0,1,1]
	v_cvt_scalef32_pk_f32_fp4 v[134:135], v23, 1.0
	v_cvt_scalef32_pk_f32_fp4 v[136:137], v23, 1.0 op_sel:[1,0,0]
	v_cvt_scalef32_pk_f32_fp4 v[138:139], v23, 1.0 op_sel:[0,1,0]
	v_cvt_scalef32_pk_f32_fp4 v[140:141], v23, 1.0 op_sel:[1,1,0]
	v_pk_fma_f32 v[118:119], v[130:131], v[134:135], v[118:119] op_sel_hi:[0,1,1]
	v_pk_fma_f32 v[116:117], v[130:131], v[136:137], v[116:117] op_sel_hi:[0,1,1]
	v_pk_fma_f32 v[114:115], v[130:131], v[138:139], v[114:115] op_sel_hi:[0,1,1]
	v_pk_fma_f32 v[112:113], v[130:131], v[140:141], v[112:113] op_sel_hi:[0,1,1]
	v_cvt_scalef32_pk_f32_fp4 v[134:135], v24, 1.0
	v_cvt_scalef32_pk_f32_fp4 v[136:137], v24, 1.0 op_sel:[1,0,0]
	v_cvt_scalef32_pk_f32_fp4 v[138:139], v24, 1.0 op_sel:[0,1,0]
	v_cvt_scalef32_pk_f32_fp4 v[140:141], v24, 1.0 op_sel:[1,1,0]
	v_pk_fma_f32 v[80:81], v[130:131], v[134:135], v[80:81] op_sel_hi:[0,1,1]
	v_pk_fma_f32 v[78:79], v[130:131], v[136:137], v[78:79] op_sel_hi:[0,1,1]
	v_pk_fma_f32 v[76:77], v[130:131], v[138:139], v[76:77] op_sel_hi:[0,1,1]
	v_pk_fma_f32 v[74:75], v[130:131], v[140:141], v[74:75] op_sel_hi:[0,1,1]
	v_cvt_scalef32_pk_f32_fp4 v[134:135], v25, 1.0
	v_cvt_scalef32_pk_f32_fp4 v[136:137], v25, 1.0 op_sel:[1,0,0]
	v_cvt_scalef32_pk_f32_fp4 v[138:139], v25, 1.0 op_sel:[0,1,0]
	v_cvt_scalef32_pk_f32_fp4 v[140:141], v25, 1.0 op_sel:[1,1,0]
	v_pk_fma_f32 v[72:73], v[130:131], v[134:135], v[72:73] op_sel_hi:[0,1,1]
	v_pk_fma_f32 v[70:71], v[130:131], v[136:137], v[70:71] op_sel_hi:[0,1,1]
	v_pk_fma_f32 v[68:69], v[130:131], v[138:139], v[68:69] op_sel_hi:[0,1,1]
	v_pk_fma_f32 v[66:67], v[130:131], v[140:141], v[66:67] op_sel_hi:[0,1,1]
	s_waitcnt vmcnt(10)
	v_cvt_scalef32_pk_f32_fp4 v[134:135], v18, 1.0
	v_cvt_scalef32_pk_f32_fp4 v[136:137], v18, 1.0 op_sel:[1,0,0]
	v_cvt_scalef32_pk_f32_fp4 v[138:139], v18, 1.0 op_sel:[0,1,0]
	v_cvt_scalef32_pk_f32_fp4 v[140:141], v18, 1.0 op_sel:[1,1,0]
	v_pk_fma_f32 v[34:35], v[130:131], v[134:135], v[34:35] op_sel_hi:[0,1,1]
	v_pk_fma_f32 v[36:37], v[130:131], v[136:137], v[36:37] op_sel_hi:[0,1,1]
	v_pk_fma_f32 v[38:39], v[130:131], v[138:139], v[38:39] op_sel_hi:[0,1,1]
	v_pk_fma_f32 v[40:41], v[130:131], v[140:141], v[40:41] op_sel_hi:[0,1,1]
	v_cvt_scalef32_pk_f32_fp4 v[134:135], v19, 1.0
	v_cvt_scalef32_pk_f32_fp4 v[136:137], v19, 1.0 op_sel:[1,0,0]
	v_cvt_scalef32_pk_f32_fp4 v[138:139], v19, 1.0 op_sel:[0,1,0]
	v_cvt_scalef32_pk_f32_fp4 v[140:141], v19, 1.0 op_sel:[1,1,0]
	v_pk_fma_f32 v[42:43], v[130:131], v[134:135], v[42:43] op_sel_hi:[0,1,1]
	v_pk_fma_f32 v[44:45], v[130:131], v[136:137], v[44:45] op_sel_hi:[0,1,1]
	v_pk_fma_f32 v[46:47], v[130:131], v[138:139], v[46:47] op_sel_hi:[0,1,1]
	v_pk_fma_f32 v[48:49], v[130:131], v[140:141], v[48:49] op_sel_hi:[0,1,1]
	v_cvt_scalef32_pk_f32_fp4 v[134:135], v20, 1.0
	v_cvt_scalef32_pk_f32_fp4 v[136:137], v20, 1.0 op_sel:[1,0,0]
	v_cvt_scalef32_pk_f32_fp4 v[138:139], v20, 1.0 op_sel:[0,1,0]
	v_cvt_scalef32_pk_f32_fp4 v[140:141], v20, 1.0 op_sel:[1,1,0]
	v_pk_fma_f32 v[50:51], v[130:131], v[134:135], v[50:51] op_sel_hi:[0,1,1]
	v_pk_fma_f32 v[52:53], v[130:131], v[136:137], v[52:53] op_sel_hi:[0,1,1]
	v_pk_fma_f32 v[54:55], v[130:131], v[138:139], v[54:55] op_sel_hi:[0,1,1]
	v_pk_fma_f32 v[56:57], v[130:131], v[140:141], v[56:57] op_sel_hi:[0,1,1]
	v_cvt_scalef32_pk_f32_fp4 v[134:135], v21, 1.0
	v_cvt_scalef32_pk_f32_fp4 v[136:137], v21, 1.0 op_sel:[1,0,0]
	v_cvt_scalef32_pk_f32_fp4 v[138:139], v21, 1.0 op_sel:[0,1,0]
	v_cvt_scalef32_pk_f32_fp4 v[140:141], v21, 1.0 op_sel:[1,1,0]
	v_pk_fma_f32 v[58:59], v[130:131], v[134:135], v[58:59] op_sel_hi:[0,1,1]
	v_pk_fma_f32 v[60:61], v[130:131], v[136:137], v[60:61] op_sel_hi:[0,1,1]
	v_pk_fma_f32 v[62:63], v[130:131], v[138:139], v[62:63] op_sel_hi:[0,1,1]
	v_pk_fma_f32 v[64:65], v[130:131], v[140:141], v[64:65] op_sel_hi:[0,1,1]
	ds_read_b32 v130, v132 offset:48
	s_waitcnt vmcnt(9)
	v_cvt_scalef32_pk_f32_fp4 v[134:135], v30, 1.0
	v_cvt_scalef32_pk_f32_fp4 v[136:137], v30, 1.0 op_sel:[1,0,0]
	v_cvt_scalef32_pk_f32_fp4 v[138:139], v30, 1.0 op_sel:[0,1,0]
	v_cvt_scalef32_pk_f32_fp4 v[140:141], v30, 1.0 op_sel:[1,1,0]
	s_waitcnt lgkmcnt(0)
	v_pk_fma_f32 v[128:129], v[130:131], v[134:135], v[128:129] op_sel_hi:[0,1,1]
	v_pk_fma_f32 v[126:127], v[130:131], v[136:137], v[126:127] op_sel_hi:[0,1,1]
	v_pk_fma_f32 v[122:123], v[130:131], v[138:139], v[122:123] op_sel_hi:[0,1,1]
	v_pk_fma_f32 v[120:121], v[130:131], v[140:141], v[120:121] op_sel_hi:[0,1,1]
	v_cvt_scalef32_pk_f32_fp4 v[134:135], v31, 1.0
	v_cvt_scalef32_pk_f32_fp4 v[136:137], v31, 1.0 op_sel:[1,0,0]
	v_cvt_scalef32_pk_f32_fp4 v[138:139], v31, 1.0 op_sel:[0,1,0]
	v_cvt_scalef32_pk_f32_fp4 v[140:141], v31, 1.0 op_sel:[1,1,0]
	v_pk_fma_f32 v[118:119], v[130:131], v[134:135], v[118:119] op_sel_hi:[0,1,1]
	v_pk_fma_f32 v[116:117], v[130:131], v[136:137], v[116:117] op_sel_hi:[0,1,1]
	v_pk_fma_f32 v[114:115], v[130:131], v[138:139], v[114:115] op_sel_hi:[0,1,1]
	v_pk_fma_f32 v[112:113], v[130:131], v[140:141], v[112:113] op_sel_hi:[0,1,1]
	v_cvt_scalef32_pk_f32_fp4 v[134:135], v32, 1.0
	v_cvt_scalef32_pk_f32_fp4 v[136:137], v32, 1.0 op_sel:[1,0,0]
	v_cvt_scalef32_pk_f32_fp4 v[138:139], v32, 1.0 op_sel:[0,1,0]
	v_cvt_scalef32_pk_f32_fp4 v[140:141], v32, 1.0 op_sel:[1,1,0]
	v_pk_fma_f32 v[80:81], v[130:131], v[134:135], v[80:81] op_sel_hi:[0,1,1]
	v_pk_fma_f32 v[78:79], v[130:131], v[136:137], v[78:79] op_sel_hi:[0,1,1]
	v_pk_fma_f32 v[76:77], v[130:131], v[138:139], v[76:77] op_sel_hi:[0,1,1]
	v_pk_fma_f32 v[74:75], v[130:131], v[140:141], v[74:75] op_sel_hi:[0,1,1]
	v_cvt_scalef32_pk_f32_fp4 v[134:135], v33, 1.0
	v_cvt_scalef32_pk_f32_fp4 v[136:137], v33, 1.0 op_sel:[1,0,0]
	v_cvt_scalef32_pk_f32_fp4 v[138:139], v33, 1.0 op_sel:[0,1,0]
	v_cvt_scalef32_pk_f32_fp4 v[140:141], v33, 1.0 op_sel:[1,1,0]
	v_pk_fma_f32 v[72:73], v[130:131], v[134:135], v[72:73] op_sel_hi:[0,1,1]
	v_pk_fma_f32 v[70:71], v[130:131], v[136:137], v[70:71] op_sel_hi:[0,1,1]
	v_pk_fma_f32 v[68:69], v[130:131], v[138:139], v[68:69] op_sel_hi:[0,1,1]
	v_pk_fma_f32 v[66:67], v[130:131], v[140:141], v[66:67] op_sel_hi:[0,1,1]
	s_waitcnt vmcnt(8)
	v_cvt_scalef32_pk_f32_fp4 v[134:135], v26, 1.0
	v_cvt_scalef32_pk_f32_fp4 v[136:137], v26, 1.0 op_sel:[1,0,0]
	v_cvt_scalef32_pk_f32_fp4 v[138:139], v26, 1.0 op_sel:[0,1,0]
	v_cvt_scalef32_pk_f32_fp4 v[140:141], v26, 1.0 op_sel:[1,1,0]
	v_pk_fma_f32 v[34:35], v[130:131], v[134:135], v[34:35] op_sel_hi:[0,1,1]
	v_pk_fma_f32 v[36:37], v[130:131], v[136:137], v[36:37] op_sel_hi:[0,1,1]
	v_pk_fma_f32 v[38:39], v[130:131], v[138:139], v[38:39] op_sel_hi:[0,1,1]
	v_pk_fma_f32 v[40:41], v[130:131], v[140:141], v[40:41] op_sel_hi:[0,1,1]
	v_cvt_scalef32_pk_f32_fp4 v[134:135], v27, 1.0
	v_cvt_scalef32_pk_f32_fp4 v[136:137], v27, 1.0 op_sel:[1,0,0]
	v_cvt_scalef32_pk_f32_fp4 v[138:139], v27, 1.0 op_sel:[0,1,0]
	v_cvt_scalef32_pk_f32_fp4 v[140:141], v27, 1.0 op_sel:[1,1,0]
	v_pk_fma_f32 v[42:43], v[130:131], v[134:135], v[42:43] op_sel_hi:[0,1,1]
	v_pk_fma_f32 v[44:45], v[130:131], v[136:137], v[44:45] op_sel_hi:[0,1,1]
	v_pk_fma_f32 v[46:47], v[130:131], v[138:139], v[46:47] op_sel_hi:[0,1,1]
	v_pk_fma_f32 v[48:49], v[130:131], v[140:141], v[48:49] op_sel_hi:[0,1,1]
	v_cvt_scalef32_pk_f32_fp4 v[134:135], v28, 1.0
	v_cvt_scalef32_pk_f32_fp4 v[136:137], v28, 1.0 op_sel:[1,0,0]
	v_cvt_scalef32_pk_f32_fp4 v[138:139], v28, 1.0 op_sel:[0,1,0]
	v_cvt_scalef32_pk_f32_fp4 v[140:141], v28, 1.0 op_sel:[1,1,0]
	v_pk_fma_f32 v[50:51], v[130:131], v[134:135], v[50:51] op_sel_hi:[0,1,1]
	v_pk_fma_f32 v[52:53], v[130:131], v[136:137], v[52:53] op_sel_hi:[0,1,1]
	v_pk_fma_f32 v[54:55], v[130:131], v[138:139], v[54:55] op_sel_hi:[0,1,1]
	v_pk_fma_f32 v[56:57], v[130:131], v[140:141], v[56:57] op_sel_hi:[0,1,1]
	v_cvt_scalef32_pk_f32_fp4 v[134:135], v29, 1.0
	v_cvt_scalef32_pk_f32_fp4 v[136:137], v29, 1.0 op_sel:[1,0,0]
	v_cvt_scalef32_pk_f32_fp4 v[138:139], v29, 1.0 op_sel:[0,1,0]
	v_cvt_scalef32_pk_f32_fp4 v[140:141], v29, 1.0 op_sel:[1,1,0]
	v_pk_fma_f32 v[58:59], v[130:131], v[134:135], v[58:59] op_sel_hi:[0,1,1]
	v_pk_fma_f32 v[60:61], v[130:131], v[136:137], v[60:61] op_sel_hi:[0,1,1]
	v_pk_fma_f32 v[62:63], v[130:131], v[138:139], v[62:63] op_sel_hi:[0,1,1]
	v_pk_fma_f32 v[64:65], v[130:131], v[140:141], v[64:65] op_sel_hi:[0,1,1]
	ds_read_b32 v130, v132 offset:64
	s_waitcnt vmcnt(7)
	v_cvt_scalef32_pk_f32_fp4 v[134:135], v142, 1.0
	v_cvt_scalef32_pk_f32_fp4 v[136:137], v142, 1.0 op_sel:[1,0,0]
	v_cvt_scalef32_pk_f32_fp4 v[138:139], v142, 1.0 op_sel:[0,1,0]
	v_cvt_scalef32_pk_f32_fp4 v[140:141], v142, 1.0 op_sel:[1,1,0]
	s_waitcnt lgkmcnt(0)
	v_pk_fma_f32 v[128:129], v[130:131], v[134:135], v[128:129] op_sel_hi:[0,1,1]
	v_pk_fma_f32 v[126:127], v[130:131], v[136:137], v[126:127] op_sel_hi:[0,1,1]
	v_pk_fma_f32 v[122:123], v[130:131], v[138:139], v[122:123] op_sel_hi:[0,1,1]
	v_pk_fma_f32 v[120:121], v[130:131], v[140:141], v[120:121] op_sel_hi:[0,1,1]
	v_cvt_scalef32_pk_f32_fp4 v[134:135], v143, 1.0
	v_cvt_scalef32_pk_f32_fp4 v[136:137], v143, 1.0 op_sel:[1,0,0]
	v_cvt_scalef32_pk_f32_fp4 v[138:139], v143, 1.0 op_sel:[0,1,0]
	v_cvt_scalef32_pk_f32_fp4 v[140:141], v143, 1.0 op_sel:[1,1,0]
	v_pk_fma_f32 v[118:119], v[130:131], v[134:135], v[118:119] op_sel_hi:[0,1,1]
	v_pk_fma_f32 v[116:117], v[130:131], v[136:137], v[116:117] op_sel_hi:[0,1,1]
	v_pk_fma_f32 v[114:115], v[130:131], v[138:139], v[114:115] op_sel_hi:[0,1,1]
	v_pk_fma_f32 v[112:113], v[130:131], v[140:141], v[112:113] op_sel_hi:[0,1,1]
	v_cvt_scalef32_pk_f32_fp4 v[134:135], v144, 1.0
	v_cvt_scalef32_pk_f32_fp4 v[136:137], v144, 1.0 op_sel:[1,0,0]
	v_cvt_scalef32_pk_f32_fp4 v[138:139], v144, 1.0 op_sel:[0,1,0]
	v_cvt_scalef32_pk_f32_fp4 v[140:141], v144, 1.0 op_sel:[1,1,0]
	v_pk_fma_f32 v[80:81], v[130:131], v[134:135], v[80:81] op_sel_hi:[0,1,1]
	v_pk_fma_f32 v[78:79], v[130:131], v[136:137], v[78:79] op_sel_hi:[0,1,1]
	v_pk_fma_f32 v[76:77], v[130:131], v[138:139], v[76:77] op_sel_hi:[0,1,1]
	v_pk_fma_f32 v[74:75], v[130:131], v[140:141], v[74:75] op_sel_hi:[0,1,1]
	v_cvt_scalef32_pk_f32_fp4 v[134:135], v145, 1.0
	v_cvt_scalef32_pk_f32_fp4 v[136:137], v145, 1.0 op_sel:[1,0,0]
	v_cvt_scalef32_pk_f32_fp4 v[138:139], v145, 1.0 op_sel:[0,1,0]
	v_cvt_scalef32_pk_f32_fp4 v[140:141], v145, 1.0 op_sel:[1,1,0]
	v_pk_fma_f32 v[72:73], v[130:131], v[134:135], v[72:73] op_sel_hi:[0,1,1]
	v_pk_fma_f32 v[70:71], v[130:131], v[136:137], v[70:71] op_sel_hi:[0,1,1]
	v_pk_fma_f32 v[68:69], v[130:131], v[138:139], v[68:69] op_sel_hi:[0,1,1]
	v_pk_fma_f32 v[66:67], v[130:131], v[140:141], v[66:67] op_sel_hi:[0,1,1]
	s_waitcnt vmcnt(6)
	v_cvt_scalef32_pk_f32_fp4 v[134:135], v146, 1.0
	v_cvt_scalef32_pk_f32_fp4 v[136:137], v146, 1.0 op_sel:[1,0,0]
	v_cvt_scalef32_pk_f32_fp4 v[138:139], v146, 1.0 op_sel:[0,1,0]
	v_cvt_scalef32_pk_f32_fp4 v[140:141], v146, 1.0 op_sel:[1,1,0]
	v_pk_fma_f32 v[34:35], v[130:131], v[134:135], v[34:35] op_sel_hi:[0,1,1]
	v_pk_fma_f32 v[36:37], v[130:131], v[136:137], v[36:37] op_sel_hi:[0,1,1]
	v_pk_fma_f32 v[38:39], v[130:131], v[138:139], v[38:39] op_sel_hi:[0,1,1]
	v_pk_fma_f32 v[40:41], v[130:131], v[140:141], v[40:41] op_sel_hi:[0,1,1]
	v_cvt_scalef32_pk_f32_fp4 v[134:135], v147, 1.0
	v_cvt_scalef32_pk_f32_fp4 v[136:137], v147, 1.0 op_sel:[1,0,0]
	v_cvt_scalef32_pk_f32_fp4 v[138:139], v147, 1.0 op_sel:[0,1,0]
	v_cvt_scalef32_pk_f32_fp4 v[140:141], v147, 1.0 op_sel:[1,1,0]
	v_pk_fma_f32 v[42:43], v[130:131], v[134:135], v[42:43] op_sel_hi:[0,1,1]
	v_pk_fma_f32 v[44:45], v[130:131], v[136:137], v[44:45] op_sel_hi:[0,1,1]
	v_pk_fma_f32 v[46:47], v[130:131], v[138:139], v[46:47] op_sel_hi:[0,1,1]
	v_pk_fma_f32 v[48:49], v[130:131], v[140:141], v[48:49] op_sel_hi:[0,1,1]
	v_cvt_scalef32_pk_f32_fp4 v[134:135], v148, 1.0
	v_cvt_scalef32_pk_f32_fp4 v[136:137], v148, 1.0 op_sel:[1,0,0]
	v_cvt_scalef32_pk_f32_fp4 v[138:139], v148, 1.0 op_sel:[0,1,0]
	v_cvt_scalef32_pk_f32_fp4 v[140:141], v148, 1.0 op_sel:[1,1,0]
	v_pk_fma_f32 v[50:51], v[130:131], v[134:135], v[50:51] op_sel_hi:[0,1,1]
	v_pk_fma_f32 v[52:53], v[130:131], v[136:137], v[52:53] op_sel_hi:[0,1,1]
	v_pk_fma_f32 v[54:55], v[130:131], v[138:139], v[54:55] op_sel_hi:[0,1,1]
	v_pk_fma_f32 v[56:57], v[130:131], v[140:141], v[56:57] op_sel_hi:[0,1,1]
	v_cvt_scalef32_pk_f32_fp4 v[134:135], v149, 1.0
	v_cvt_scalef32_pk_f32_fp4 v[136:137], v149, 1.0 op_sel:[1,0,0]
	v_cvt_scalef32_pk_f32_fp4 v[138:139], v149, 1.0 op_sel:[0,1,0]
	v_cvt_scalef32_pk_f32_fp4 v[140:141], v149, 1.0 op_sel:[1,1,0]
	v_pk_fma_f32 v[58:59], v[130:131], v[134:135], v[58:59] op_sel_hi:[0,1,1]
	v_pk_fma_f32 v[60:61], v[130:131], v[136:137], v[60:61] op_sel_hi:[0,1,1]
	v_pk_fma_f32 v[62:63], v[130:131], v[138:139], v[62:63] op_sel_hi:[0,1,1]
	v_pk_fma_f32 v[64:65], v[130:131], v[140:141], v[64:65] op_sel_hi:[0,1,1]
	ds_read_b32 v130, v132 offset:80
	s_waitcnt vmcnt(5)
	v_cvt_scalef32_pk_f32_fp4 v[134:135], v150, 1.0
	v_cvt_scalef32_pk_f32_fp4 v[136:137], v150, 1.0 op_sel:[1,0,0]
	v_cvt_scalef32_pk_f32_fp4 v[138:139], v150, 1.0 op_sel:[0,1,0]
	v_cvt_scalef32_pk_f32_fp4 v[140:141], v150, 1.0 op_sel:[1,1,0]
	s_waitcnt lgkmcnt(0)
	v_pk_fma_f32 v[128:129], v[130:131], v[134:135], v[128:129] op_sel_hi:[0,1,1]
	v_pk_fma_f32 v[126:127], v[130:131], v[136:137], v[126:127] op_sel_hi:[0,1,1]
	v_pk_fma_f32 v[122:123], v[130:131], v[138:139], v[122:123] op_sel_hi:[0,1,1]
	v_pk_fma_f32 v[120:121], v[130:131], v[140:141], v[120:121] op_sel_hi:[0,1,1]
	v_cvt_scalef32_pk_f32_fp4 v[134:135], v151, 1.0
	v_cvt_scalef32_pk_f32_fp4 v[136:137], v151, 1.0 op_sel:[1,0,0]
	v_cvt_scalef32_pk_f32_fp4 v[138:139], v151, 1.0 op_sel:[0,1,0]
	v_cvt_scalef32_pk_f32_fp4 v[140:141], v151, 1.0 op_sel:[1,1,0]
	v_pk_fma_f32 v[118:119], v[130:131], v[134:135], v[118:119] op_sel_hi:[0,1,1]
	v_pk_fma_f32 v[116:117], v[130:131], v[136:137], v[116:117] op_sel_hi:[0,1,1]
	v_pk_fma_f32 v[114:115], v[130:131], v[138:139], v[114:115] op_sel_hi:[0,1,1]
	v_pk_fma_f32 v[112:113], v[130:131], v[140:141], v[112:113] op_sel_hi:[0,1,1]
	v_cvt_scalef32_pk_f32_fp4 v[134:135], v152, 1.0
	v_cvt_scalef32_pk_f32_fp4 v[136:137], v152, 1.0 op_sel:[1,0,0]
	v_cvt_scalef32_pk_f32_fp4 v[138:139], v152, 1.0 op_sel:[0,1,0]
	v_cvt_scalef32_pk_f32_fp4 v[140:141], v152, 1.0 op_sel:[1,1,0]
	v_pk_fma_f32 v[80:81], v[130:131], v[134:135], v[80:81] op_sel_hi:[0,1,1]
	v_pk_fma_f32 v[78:79], v[130:131], v[136:137], v[78:79] op_sel_hi:[0,1,1]
	v_pk_fma_f32 v[76:77], v[130:131], v[138:139], v[76:77] op_sel_hi:[0,1,1]
	v_pk_fma_f32 v[74:75], v[130:131], v[140:141], v[74:75] op_sel_hi:[0,1,1]
	v_cvt_scalef32_pk_f32_fp4 v[134:135], v153, 1.0
	v_cvt_scalef32_pk_f32_fp4 v[136:137], v153, 1.0 op_sel:[1,0,0]
	v_cvt_scalef32_pk_f32_fp4 v[138:139], v153, 1.0 op_sel:[0,1,0]
	v_cvt_scalef32_pk_f32_fp4 v[140:141], v153, 1.0 op_sel:[1,1,0]
	v_pk_fma_f32 v[72:73], v[130:131], v[134:135], v[72:73] op_sel_hi:[0,1,1]
	v_pk_fma_f32 v[70:71], v[130:131], v[136:137], v[70:71] op_sel_hi:[0,1,1]
	v_pk_fma_f32 v[68:69], v[130:131], v[138:139], v[68:69] op_sel_hi:[0,1,1]
	v_pk_fma_f32 v[66:67], v[130:131], v[140:141], v[66:67] op_sel_hi:[0,1,1]
	s_waitcnt vmcnt(4)
	v_cvt_scalef32_pk_f32_fp4 v[134:135], v232, 1.0
	v_cvt_scalef32_pk_f32_fp4 v[136:137], v232, 1.0 op_sel:[1,0,0]
	v_cvt_scalef32_pk_f32_fp4 v[138:139], v232, 1.0 op_sel:[0,1,0]
	v_cvt_scalef32_pk_f32_fp4 v[140:141], v232, 1.0 op_sel:[1,1,0]
	v_pk_fma_f32 v[34:35], v[130:131], v[134:135], v[34:35] op_sel_hi:[0,1,1]
	v_pk_fma_f32 v[36:37], v[130:131], v[136:137], v[36:37] op_sel_hi:[0,1,1]
	v_pk_fma_f32 v[38:39], v[130:131], v[138:139], v[38:39] op_sel_hi:[0,1,1]
	v_pk_fma_f32 v[40:41], v[130:131], v[140:141], v[40:41] op_sel_hi:[0,1,1]
	v_cvt_scalef32_pk_f32_fp4 v[134:135], v233, 1.0
	v_cvt_scalef32_pk_f32_fp4 v[136:137], v233, 1.0 op_sel:[1,0,0]
	v_cvt_scalef32_pk_f32_fp4 v[138:139], v233, 1.0 op_sel:[0,1,0]
	v_cvt_scalef32_pk_f32_fp4 v[140:141], v233, 1.0 op_sel:[1,1,0]
	v_pk_fma_f32 v[42:43], v[130:131], v[134:135], v[42:43] op_sel_hi:[0,1,1]
	v_pk_fma_f32 v[44:45], v[130:131], v[136:137], v[44:45] op_sel_hi:[0,1,1]
	v_pk_fma_f32 v[46:47], v[130:131], v[138:139], v[46:47] op_sel_hi:[0,1,1]
	v_pk_fma_f32 v[48:49], v[130:131], v[140:141], v[48:49] op_sel_hi:[0,1,1]
	v_cvt_scalef32_pk_f32_fp4 v[134:135], v234, 1.0
	v_cvt_scalef32_pk_f32_fp4 v[136:137], v234, 1.0 op_sel:[1,0,0]
	v_cvt_scalef32_pk_f32_fp4 v[138:139], v234, 1.0 op_sel:[0,1,0]
	v_cvt_scalef32_pk_f32_fp4 v[140:141], v234, 1.0 op_sel:[1,1,0]
	v_pk_fma_f32 v[50:51], v[130:131], v[134:135], v[50:51] op_sel_hi:[0,1,1]
	v_pk_fma_f32 v[52:53], v[130:131], v[136:137], v[52:53] op_sel_hi:[0,1,1]
	v_pk_fma_f32 v[54:55], v[130:131], v[138:139], v[54:55] op_sel_hi:[0,1,1]
	v_pk_fma_f32 v[56:57], v[130:131], v[140:141], v[56:57] op_sel_hi:[0,1,1]
	v_cvt_scalef32_pk_f32_fp4 v[134:135], v235, 1.0
	v_cvt_scalef32_pk_f32_fp4 v[136:137], v235, 1.0 op_sel:[1,0,0]
	v_cvt_scalef32_pk_f32_fp4 v[138:139], v235, 1.0 op_sel:[0,1,0]
	v_cvt_scalef32_pk_f32_fp4 v[140:141], v235, 1.0 op_sel:[1,1,0]
	v_pk_fma_f32 v[58:59], v[130:131], v[134:135], v[58:59] op_sel_hi:[0,1,1]
	v_pk_fma_f32 v[60:61], v[130:131], v[136:137], v[60:61] op_sel_hi:[0,1,1]
	v_pk_fma_f32 v[62:63], v[130:131], v[138:139], v[62:63] op_sel_hi:[0,1,1]
	v_pk_fma_f32 v[64:65], v[130:131], v[140:141], v[64:65] op_sel_hi:[0,1,1]
	ds_read_b32 v130, v132 offset:96
	s_waitcnt vmcnt(3)
	v_cvt_scalef32_pk_f32_fp4 v[134:135], v236, 1.0
	v_cvt_scalef32_pk_f32_fp4 v[136:137], v236, 1.0 op_sel:[1,0,0]
	v_cvt_scalef32_pk_f32_fp4 v[138:139], v236, 1.0 op_sel:[0,1,0]
	v_cvt_scalef32_pk_f32_fp4 v[140:141], v236, 1.0 op_sel:[1,1,0]
	s_waitcnt lgkmcnt(0)
	v_pk_fma_f32 v[128:129], v[130:131], v[134:135], v[128:129] op_sel_hi:[0,1,1]
	v_pk_fma_f32 v[126:127], v[130:131], v[136:137], v[126:127] op_sel_hi:[0,1,1]
	v_pk_fma_f32 v[122:123], v[130:131], v[138:139], v[122:123] op_sel_hi:[0,1,1]
	v_pk_fma_f32 v[120:121], v[130:131], v[140:141], v[120:121] op_sel_hi:[0,1,1]
	v_cvt_scalef32_pk_f32_fp4 v[134:135], v237, 1.0
	v_cvt_scalef32_pk_f32_fp4 v[136:137], v237, 1.0 op_sel:[1,0,0]
	v_cvt_scalef32_pk_f32_fp4 v[138:139], v237, 1.0 op_sel:[0,1,0]
	v_cvt_scalef32_pk_f32_fp4 v[140:141], v237, 1.0 op_sel:[1,1,0]
	v_pk_fma_f32 v[118:119], v[130:131], v[134:135], v[118:119] op_sel_hi:[0,1,1]
	v_pk_fma_f32 v[116:117], v[130:131], v[136:137], v[116:117] op_sel_hi:[0,1,1]
	v_pk_fma_f32 v[114:115], v[130:131], v[138:139], v[114:115] op_sel_hi:[0,1,1]
	v_pk_fma_f32 v[112:113], v[130:131], v[140:141], v[112:113] op_sel_hi:[0,1,1]
	v_cvt_scalef32_pk_f32_fp4 v[134:135], v238, 1.0
	v_cvt_scalef32_pk_f32_fp4 v[136:137], v238, 1.0 op_sel:[1,0,0]
	v_cvt_scalef32_pk_f32_fp4 v[138:139], v238, 1.0 op_sel:[0,1,0]
	v_cvt_scalef32_pk_f32_fp4 v[140:141], v238, 1.0 op_sel:[1,1,0]
	v_pk_fma_f32 v[80:81], v[130:131], v[134:135], v[80:81] op_sel_hi:[0,1,1]
	v_pk_fma_f32 v[78:79], v[130:131], v[136:137], v[78:79] op_sel_hi:[0,1,1]
	v_pk_fma_f32 v[76:77], v[130:131], v[138:139], v[76:77] op_sel_hi:[0,1,1]
	v_pk_fma_f32 v[74:75], v[130:131], v[140:141], v[74:75] op_sel_hi:[0,1,1]
	v_cvt_scalef32_pk_f32_fp4 v[134:135], v239, 1.0
	v_cvt_scalef32_pk_f32_fp4 v[136:137], v239, 1.0 op_sel:[1,0,0]
	v_cvt_scalef32_pk_f32_fp4 v[138:139], v239, 1.0 op_sel:[0,1,0]
	v_cvt_scalef32_pk_f32_fp4 v[140:141], v239, 1.0 op_sel:[1,1,0]
	v_pk_fma_f32 v[72:73], v[130:131], v[134:135], v[72:73] op_sel_hi:[0,1,1]
	v_pk_fma_f32 v[70:71], v[130:131], v[136:137], v[70:71] op_sel_hi:[0,1,1]
	v_pk_fma_f32 v[68:69], v[130:131], v[138:139], v[68:69] op_sel_hi:[0,1,1]
	v_pk_fma_f32 v[66:67], v[130:131], v[140:141], v[66:67] op_sel_hi:[0,1,1]
	s_waitcnt vmcnt(2)
	v_cvt_scalef32_pk_f32_fp4 v[134:135], v240, 1.0
	v_cvt_scalef32_pk_f32_fp4 v[136:137], v240, 1.0 op_sel:[1,0,0]
	v_cvt_scalef32_pk_f32_fp4 v[138:139], v240, 1.0 op_sel:[0,1,0]
	v_cvt_scalef32_pk_f32_fp4 v[140:141], v240, 1.0 op_sel:[1,1,0]
	v_pk_fma_f32 v[34:35], v[130:131], v[134:135], v[34:35] op_sel_hi:[0,1,1]
	v_pk_fma_f32 v[36:37], v[130:131], v[136:137], v[36:37] op_sel_hi:[0,1,1]
	v_pk_fma_f32 v[38:39], v[130:131], v[138:139], v[38:39] op_sel_hi:[0,1,1]
	v_pk_fma_f32 v[40:41], v[130:131], v[140:141], v[40:41] op_sel_hi:[0,1,1]
	v_cvt_scalef32_pk_f32_fp4 v[134:135], v241, 1.0
	v_cvt_scalef32_pk_f32_fp4 v[136:137], v241, 1.0 op_sel:[1,0,0]
	v_cvt_scalef32_pk_f32_fp4 v[138:139], v241, 1.0 op_sel:[0,1,0]
	v_cvt_scalef32_pk_f32_fp4 v[140:141], v241, 1.0 op_sel:[1,1,0]
	v_pk_fma_f32 v[42:43], v[130:131], v[134:135], v[42:43] op_sel_hi:[0,1,1]
	v_pk_fma_f32 v[44:45], v[130:131], v[136:137], v[44:45] op_sel_hi:[0,1,1]
	v_pk_fma_f32 v[46:47], v[130:131], v[138:139], v[46:47] op_sel_hi:[0,1,1]
	v_pk_fma_f32 v[48:49], v[130:131], v[140:141], v[48:49] op_sel_hi:[0,1,1]
	v_cvt_scalef32_pk_f32_fp4 v[134:135], v242, 1.0
	v_cvt_scalef32_pk_f32_fp4 v[136:137], v242, 1.0 op_sel:[1,0,0]
	v_cvt_scalef32_pk_f32_fp4 v[138:139], v242, 1.0 op_sel:[0,1,0]
	v_cvt_scalef32_pk_f32_fp4 v[140:141], v242, 1.0 op_sel:[1,1,0]
	v_pk_fma_f32 v[50:51], v[130:131], v[134:135], v[50:51] op_sel_hi:[0,1,1]
	v_pk_fma_f32 v[52:53], v[130:131], v[136:137], v[52:53] op_sel_hi:[0,1,1]
	v_pk_fma_f32 v[54:55], v[130:131], v[138:139], v[54:55] op_sel_hi:[0,1,1]
	v_pk_fma_f32 v[56:57], v[130:131], v[140:141], v[56:57] op_sel_hi:[0,1,1]
	v_cvt_scalef32_pk_f32_fp4 v[134:135], v243, 1.0
	v_cvt_scalef32_pk_f32_fp4 v[136:137], v243, 1.0 op_sel:[1,0,0]
	v_cvt_scalef32_pk_f32_fp4 v[138:139], v243, 1.0 op_sel:[0,1,0]
	v_cvt_scalef32_pk_f32_fp4 v[140:141], v243, 1.0 op_sel:[1,1,0]
	v_pk_fma_f32 v[58:59], v[130:131], v[134:135], v[58:59] op_sel_hi:[0,1,1]
	v_pk_fma_f32 v[60:61], v[130:131], v[136:137], v[60:61] op_sel_hi:[0,1,1]
	v_pk_fma_f32 v[62:63], v[130:131], v[138:139], v[62:63] op_sel_hi:[0,1,1]
	v_pk_fma_f32 v[64:65], v[130:131], v[140:141], v[64:65] op_sel_hi:[0,1,1]
	ds_read_b32 v130, v132 offset:112
	s_waitcnt vmcnt(1)
	v_cvt_scalef32_pk_f32_fp4 v[134:135], v244, 1.0
	v_cvt_scalef32_pk_f32_fp4 v[136:137], v244, 1.0 op_sel:[1,0,0]
	v_cvt_scalef32_pk_f32_fp4 v[138:139], v244, 1.0 op_sel:[0,1,0]
	v_cvt_scalef32_pk_f32_fp4 v[140:141], v244, 1.0 op_sel:[1,1,0]
	s_waitcnt lgkmcnt(0)
	v_pk_fma_f32 v[128:129], v[130:131], v[134:135], v[128:129] op_sel_hi:[0,1,1]
	v_pk_fma_f32 v[126:127], v[130:131], v[136:137], v[126:127] op_sel_hi:[0,1,1]
	v_pk_fma_f32 v[122:123], v[130:131], v[138:139], v[122:123] op_sel_hi:[0,1,1]
	v_pk_fma_f32 v[120:121], v[130:131], v[140:141], v[120:121] op_sel_hi:[0,1,1]
	v_cvt_scalef32_pk_f32_fp4 v[134:135], v245, 1.0
	v_cvt_scalef32_pk_f32_fp4 v[136:137], v245, 1.0 op_sel:[1,0,0]
	v_cvt_scalef32_pk_f32_fp4 v[138:139], v245, 1.0 op_sel:[0,1,0]
	v_cvt_scalef32_pk_f32_fp4 v[140:141], v245, 1.0 op_sel:[1,1,0]
	v_pk_fma_f32 v[118:119], v[130:131], v[134:135], v[118:119] op_sel_hi:[0,1,1]
	v_pk_fma_f32 v[116:117], v[130:131], v[136:137], v[116:117] op_sel_hi:[0,1,1]
	v_pk_fma_f32 v[114:115], v[130:131], v[138:139], v[114:115] op_sel_hi:[0,1,1]
	v_pk_fma_f32 v[112:113], v[130:131], v[140:141], v[112:113] op_sel_hi:[0,1,1]
	v_cvt_scalef32_pk_f32_fp4 v[134:135], v246, 1.0
	v_cvt_scalef32_pk_f32_fp4 v[136:137], v246, 1.0 op_sel:[1,0,0]
	v_cvt_scalef32_pk_f32_fp4 v[138:139], v246, 1.0 op_sel:[0,1,0]
	v_cvt_scalef32_pk_f32_fp4 v[140:141], v246, 1.0 op_sel:[1,1,0]
	v_pk_fma_f32 v[80:81], v[130:131], v[134:135], v[80:81] op_sel_hi:[0,1,1]
	v_pk_fma_f32 v[78:79], v[130:131], v[136:137], v[78:79] op_sel_hi:[0,1,1]
	v_pk_fma_f32 v[76:77], v[130:131], v[138:139], v[76:77] op_sel_hi:[0,1,1]
	v_pk_fma_f32 v[74:75], v[130:131], v[140:141], v[74:75] op_sel_hi:[0,1,1]
	v_cvt_scalef32_pk_f32_fp4 v[134:135], v247, 1.0
	v_cvt_scalef32_pk_f32_fp4 v[136:137], v247, 1.0 op_sel:[1,0,0]
	v_cvt_scalef32_pk_f32_fp4 v[138:139], v247, 1.0 op_sel:[0,1,0]
	v_cvt_scalef32_pk_f32_fp4 v[140:141], v247, 1.0 op_sel:[1,1,0]
	v_pk_fma_f32 v[72:73], v[130:131], v[134:135], v[72:73] op_sel_hi:[0,1,1]
	v_pk_fma_f32 v[70:71], v[130:131], v[136:137], v[70:71] op_sel_hi:[0,1,1]
	v_pk_fma_f32 v[68:69], v[130:131], v[138:139], v[68:69] op_sel_hi:[0,1,1]
	v_pk_fma_f32 v[66:67], v[130:131], v[140:141], v[66:67] op_sel_hi:[0,1,1]
	s_waitcnt vmcnt(0)
	v_cvt_scalef32_pk_f32_fp4 v[134:135], v228, 1.0
	v_cvt_scalef32_pk_f32_fp4 v[136:137], v228, 1.0 op_sel:[1,0,0]
	v_cvt_scalef32_pk_f32_fp4 v[138:139], v228, 1.0 op_sel:[0,1,0]
	v_cvt_scalef32_pk_f32_fp4 v[140:141], v228, 1.0 op_sel:[1,1,0]
	v_pk_fma_f32 v[34:35], v[130:131], v[134:135], v[34:35] op_sel_hi:[0,1,1]
	v_pk_fma_f32 v[36:37], v[130:131], v[136:137], v[36:37] op_sel_hi:[0,1,1]
	v_pk_fma_f32 v[38:39], v[130:131], v[138:139], v[38:39] op_sel_hi:[0,1,1]
	v_pk_fma_f32 v[40:41], v[130:131], v[140:141], v[40:41] op_sel_hi:[0,1,1]
	v_cvt_scalef32_pk_f32_fp4 v[134:135], v229, 1.0
	v_cvt_scalef32_pk_f32_fp4 v[136:137], v229, 1.0 op_sel:[1,0,0]
	v_cvt_scalef32_pk_f32_fp4 v[138:139], v229, 1.0 op_sel:[0,1,0]
	v_cvt_scalef32_pk_f32_fp4 v[140:141], v229, 1.0 op_sel:[1,1,0]
	v_pk_fma_f32 v[42:43], v[130:131], v[134:135], v[42:43] op_sel_hi:[0,1,1]
	v_pk_fma_f32 v[44:45], v[130:131], v[136:137], v[44:45] op_sel_hi:[0,1,1]
	v_pk_fma_f32 v[46:47], v[130:131], v[138:139], v[46:47] op_sel_hi:[0,1,1]
	v_pk_fma_f32 v[48:49], v[130:131], v[140:141], v[48:49] op_sel_hi:[0,1,1]
	v_cvt_scalef32_pk_f32_fp4 v[134:135], v230, 1.0
	v_cvt_scalef32_pk_f32_fp4 v[136:137], v230, 1.0 op_sel:[1,0,0]
	v_cvt_scalef32_pk_f32_fp4 v[138:139], v230, 1.0 op_sel:[0,1,0]
	v_cvt_scalef32_pk_f32_fp4 v[140:141], v230, 1.0 op_sel:[1,1,0]
	v_pk_fma_f32 v[50:51], v[130:131], v[134:135], v[50:51] op_sel_hi:[0,1,1]
	v_pk_fma_f32 v[52:53], v[130:131], v[136:137], v[52:53] op_sel_hi:[0,1,1]
	v_pk_fma_f32 v[54:55], v[130:131], v[138:139], v[54:55] op_sel_hi:[0,1,1]
	v_pk_fma_f32 v[56:57], v[130:131], v[140:141], v[56:57] op_sel_hi:[0,1,1]
	v_cvt_scalef32_pk_f32_fp4 v[134:135], v231, 1.0
	v_cvt_scalef32_pk_f32_fp4 v[136:137], v231, 1.0 op_sel:[1,0,0]
	v_cvt_scalef32_pk_f32_fp4 v[138:139], v231, 1.0 op_sel:[0,1,0]
	v_cvt_scalef32_pk_f32_fp4 v[140:141], v231, 1.0 op_sel:[1,1,0]
	v_pk_fma_f32 v[58:59], v[130:131], v[134:135], v[58:59] op_sel_hi:[0,1,1]
	v_pk_fma_f32 v[60:61], v[130:131], v[136:137], v[60:61] op_sel_hi:[0,1,1]
	v_pk_fma_f32 v[62:63], v[130:131], v[138:139], v[62:63] op_sel_hi:[0,1,1]
	v_pk_fma_f32 v[64:65], v[130:131], v[140:141], v[64:65] op_sel_hi:[0,1,1]
	v_lshrrev_b32_e32 v2, 1, v125
	v_and_b32_e32 v3, 1, v125
	v_lshlrev_b32_e32 v2, 9, v2
	v_lshl_add_u32 v2, v3, 4, v2
	v_lshlrev_b64 v[94:95], 10, v[94:95]
	v_or_b32_e32 v94, v94, v82
	v_add_u32_e32 v94, v94, v2
	v_lshlrev_b64 v[130:131], 2, v[94:95]
	v_lshl_add_u64 v[132:133], s[18:19], 0, v[130:131]
	global_load_dwordx4 v[4:7], v[132:133], off
	global_load_dwordx4 v[8:11], v[132:133], off offset:16
	global_load_dwordx4 v[12:15], v[132:133], off offset:32
	global_load_dwordx4 v[16:19], v[132:133], off offset:48
	v_lshlrev_b32_e32 v2, 2, v2
	v_mov_b32_e32 v3, 0
	v_lshl_add_u64 v[20:21], v[88:89], 0, v[2:3]
	global_load_dwordx4 v[134:137], v[20:21], off
	global_load_dwordx4 v[138:141], v[20:21], off offset:16
	global_load_dwordx4 v[142:145], v[20:21], off offset:32
	global_load_dwordx4 v[146:149], v[20:21], off offset:48
	v_readlane_b32 s60, v254, 29
	v_readlane_b32 s61, v254, 30
	v_readlane_b32 s62, v254, 31
	v_readlane_b32 s63, v254, 32
	v_lshl_add_u64 v[22:23], s[20:21], 0, v[130:131]
	v_lshl_add_u64 v[26:27], v[94:95], 1, s[16:17]
	v_permlane16_swap_b32_e32 v128, v80
	v_permlane16_swap_b32_e32 v129, v81
	v_pk_add_f32 v[128:129], v[128:129], v[80:81]
	v_permlane16_swap_b32_e32 v126, v78
	v_permlane16_swap_b32_e32 v127, v79
	v_pk_add_f32 v[126:127], v[126:127], v[78:79]
	v_permlane16_swap_b32_e32 v122, v76
	v_permlane16_swap_b32_e32 v123, v77
	v_pk_add_f32 v[122:123], v[122:123], v[76:77]
	v_permlane16_swap_b32_e32 v120, v74
	v_permlane16_swap_b32_e32 v121, v75
	v_pk_add_f32 v[120:121], v[120:121], v[74:75]
	v_permlane16_swap_b32_e32 v118, v72
	v_permlane16_swap_b32_e32 v119, v73
	v_pk_add_f32 v[118:119], v[118:119], v[72:73]
	v_permlane16_swap_b32_e32 v116, v70
	v_permlane16_swap_b32_e32 v117, v71
	v_pk_add_f32 v[116:117], v[116:117], v[70:71]
	v_permlane16_swap_b32_e32 v114, v68
	v_permlane16_swap_b32_e32 v115, v69
	v_pk_add_f32 v[114:115], v[114:115], v[68:69]
	v_permlane16_swap_b32_e32 v112, v66
	v_permlane16_swap_b32_e32 v113, v67
	v_pk_add_f32 v[112:113], v[112:113], v[66:67]
	v_permlane16_swap_b32_e32 v34, v50
	v_permlane16_swap_b32_e32 v35, v51
	v_pk_add_f32 v[34:35], v[34:35], v[50:51]
	v_permlane16_swap_b32_e32 v36, v52
	v_permlane16_swap_b32_e32 v37, v53
	v_pk_add_f32 v[36:37], v[36:37], v[52:53]
	v_permlane16_swap_b32_e32 v38, v54
	v_permlane16_swap_b32_e32 v39, v55
	v_pk_add_f32 v[38:39], v[38:39], v[54:55]
	v_permlane16_swap_b32_e32 v40, v56
	v_permlane16_swap_b32_e32 v41, v57
	v_pk_add_f32 v[40:41], v[40:41], v[56:57]
	v_permlane16_swap_b32_e32 v42, v58
	v_permlane16_swap_b32_e32 v43, v59
	v_pk_add_f32 v[42:43], v[42:43], v[58:59]
	v_permlane16_swap_b32_e32 v44, v60
	v_permlane16_swap_b32_e32 v45, v61
	v_pk_add_f32 v[44:45], v[44:45], v[60:61]
	v_permlane16_swap_b32_e32 v46, v62
	v_permlane16_swap_b32_e32 v47, v63
	v_pk_add_f32 v[46:47], v[46:47], v[62:63]
	v_permlane16_swap_b32_e32 v48, v64
	v_permlane16_swap_b32_e32 v49, v65
	v_pk_add_f32 v[48:49], v[48:49], v[64:65]
	v_permlane32_swap_b32_e32 v128, v34
	v_permlane32_swap_b32_e32 v129, v35
	v_pk_add_f32 v[128:129], v[128:129], v[34:35]
	v_permlane32_swap_b32_e32 v126, v36
	v_permlane32_swap_b32_e32 v127, v37
	v_pk_add_f32 v[126:127], v[126:127], v[36:37]
	v_permlane32_swap_b32_e32 v122, v38
	v_permlane32_swap_b32_e32 v123, v39
	v_pk_add_f32 v[122:123], v[122:123], v[38:39]
	v_permlane32_swap_b32_e32 v120, v40
	v_permlane32_swap_b32_e32 v121, v41
	v_pk_add_f32 v[120:121], v[120:121], v[40:41]
	v_permlane32_swap_b32_e32 v118, v42
	v_permlane32_swap_b32_e32 v119, v43
	v_pk_add_f32 v[118:119], v[118:119], v[42:43]
	v_permlane32_swap_b32_e32 v116, v44
	v_permlane32_swap_b32_e32 v117, v45
	v_pk_add_f32 v[116:117], v[116:117], v[44:45]
	v_permlane32_swap_b32_e32 v114, v46
	v_permlane32_swap_b32_e32 v115, v47
	v_pk_add_f32 v[114:115], v[114:115], v[46:47]
	v_permlane32_swap_b32_e32 v112, v48
	v_permlane32_swap_b32_e32 v113, v49
	v_pk_add_f32 v[112:113], v[112:113], v[48:49]
	v_lshl_add_u64 v[24:25], s[60:61], 0, v[130:131]
	s_waitcnt vmcnt(4)
	v_pk_add_f32 v[228:229], v[4:5], v[128:129]
	v_pk_add_f32 v[230:231], v[6:7], v[126:127]
	v_pk_add_f32 v[232:233], v[8:9], v[122:123]
	v_pk_add_f32 v[234:235], v[10:11], v[120:121]
	v_pk_add_f32 v[236:237], v[12:13], v[118:119]
	v_pk_add_f32 v[238:239], v[14:15], v[116:117]
	v_pk_add_f32 v[240:241], v[16:17], v[114:115]
	v_pk_add_f32 v[242:243], v[18:19], v[112:113]
	v_pk_mul_f32 v[244:245], v[228:229], v[228:229]
	v_pk_fma_f32 v[244:245], v[230:231], v[230:231], v[244:245]
	v_pk_fma_f32 v[244:245], v[232:233], v[232:233], v[244:245]
	v_pk_fma_f32 v[244:245], v[234:235], v[234:235], v[244:245]
	v_pk_fma_f32 v[244:245], v[236:237], v[236:237], v[244:245]
	v_pk_fma_f32 v[244:245], v[238:239], v[238:239], v[244:245]
	v_pk_fma_f32 v[244:245], v[240:241], v[240:241], v[244:245]
	v_pk_fma_f32 v[244:245], v[242:243], v[242:243], v[244:245]
	v_add_f32_e32 v244, v244, v245
	ds_bpermute_b32 v245, v207, v244
	s_waitcnt lgkmcnt(0)
	v_add_f32_e32 v244, v244, v245
	ds_bpermute_b32 v245, v208, v244
	s_waitcnt lgkmcnt(0)
	v_add_f32_e32 v244, v244, v245
	ds_bpermute_b32 v245, v209, v244
	s_waitcnt lgkmcnt(0)
	v_add_f32_e32 v244, v244, v245
	ds_bpermute_b32 v245, v210, v244
	s_waitcnt lgkmcnt(0)
	v_add_f32_e32 v244, v244, v245
	ds_bpermute_b32 v245, v211, v244
	s_waitcnt lgkmcnt(0)
	v_add_f32_e32 v244, v244, v245
	ds_bpermute_b32 v245, v212, v244
	s_waitcnt lgkmcnt(0)
	v_add_f32_e32 v244, v244, v245
	v_fmamk_f32 v244, v244, 0x3a800000, v172
	v_mul_f32_e32 v245, 0x4b800000, v244
	v_cmp_gt_f32_e32 vcc, s96, v244
	s_nop 1
	v_cndmask_b32_e32 v244, v244, v245, vcc
	v_rsq_f32_e32 v244, v244
	s_nop 0
	v_mul_f32_e32 v245, 0x45800000, v244
	v_cndmask_b32_e32 v246, v244, v245, vcc
	s_waitcnt vmcnt(0)
	v_pk_mul_f32 v[134:135], v[246:247], v[134:135] op_sel_hi:[0,1]
	v_pk_mul_f32 v[136:137], v[246:247], v[136:137] op_sel_hi:[0,1]
	v_pk_mul_f32 v[138:139], v[246:247], v[138:139] op_sel_hi:[0,1]
	v_pk_mul_f32 v[140:141], v[246:247], v[140:141] op_sel_hi:[0,1]
	v_pk_mul_f32 v[142:143], v[246:247], v[142:143] op_sel_hi:[0,1]
	v_pk_mul_f32 v[144:145], v[246:247], v[144:145] op_sel_hi:[0,1]
	v_pk_mul_f32 v[146:147], v[246:247], v[146:147] op_sel_hi:[0,1]
	v_pk_mul_f32 v[148:149], v[246:247], v[148:149] op_sel_hi:[0,1]
	v_pk_mul_f32 v[134:135], v[228:229], v[134:135]
	v_pk_mul_f32 v[136:137], v[230:231], v[136:137]
	v_pk_mul_f32 v[138:139], v[232:233], v[138:139]
	v_pk_mul_f32 v[140:141], v[234:235], v[140:141]
	v_pk_mul_f32 v[142:143], v[236:237], v[142:143]
	v_pk_mul_f32 v[144:145], v[238:239], v[144:145]
	v_pk_mul_f32 v[146:147], v[240:241], v[146:147]
	v_pk_mul_f32 v[148:149], v[242:243], v[148:149]
	s_andn2_b64 vcc, exec, s[22:23]
	s_cbranch_vccnz .Lpe_mid
	global_store_dwordx4 v[24:25], v[134:137], off
	global_store_dwordx4 v[24:25], v[138:141], off offset:16
	global_store_dwordx4 v[24:25], v[142:145], off offset:32
	global_store_dwordx4 v[24:25], v[146:149], off offset:48
	s_branch .Lpe_done
.Lpe_mid:
	global_store_dwordx4 v[22:23], v[228:231], off
	global_store_dwordx4 v[22:23], v[232:235], off offset:16
	global_store_dwordx4 v[22:23], v[236:239], off offset:32
	global_store_dwordx4 v[22:23], v[240:243], off offset:48
	v_cvt_pk_bf16_f32 v150, v134, v135
	v_cvt_pk_bf16_f32 v151, v136, v137
	v_cvt_pk_bf16_f32 v152, v138, v139
	v_cvt_pk_bf16_f32 v153, v140, v141
	v_cvt_pk_bf16_f32 v196, v142, v143
	v_cvt_pk_bf16_f32 v197, v144, v145
	v_cvt_pk_bf16_f32 v198, v146, v147
	v_cvt_pk_bf16_f32 v199, v148, v149
	global_store_dwordx4 v[26:27], v[150:153], off
	global_store_dwordx4 v[26:27], v[196:199], off offset:16
.Lpe_done:
	s_mov_b64 s[6:7], exec
	s_branch .LBB0_140
